# opt35: opt26 + nt hint on the f32 residual loads of the G2/G6/G8 epilogues
# baseline (speedup 1.0000x reference)
; __device__ __forceinline__ unsigned cvt_pk_bf16(float lo, float hi) { f32x2_t v = {lo, hi}; bf16x2_t b = __builtin_convertvector(v, bf16x2_t); return __builtin_bit_cast(unsigned, b); }
;     __device__ __forceinline__ void operator()(const Acc& acc, const Unit& u, int wr, int wc, int fr, int fq) const {
;     ...
;                 const int row = row0 + ai * HALF + m * 16; float sq = 0.f;
; #pragma unroll
;                 for (int bj = 0; bj < 2; ++bj) {
;                     const size_t off = (size_t)row * DM + col0 + bj * HALF;
;                     const f32x4 b0 = *(const f32x4*)(base + off), b1 = *(const f32x4*)(base + off + 4);
;                     const f32x4 x0 = b0 + acc[ai][bj][m][0] * alpha, x1 = b1 + acc[ai][bj][m][1] * alpha;
;                     __builtin_nontemporal_store(x0, (f32x4*)(out + off)); __builtin_nontemporal_store(x1, (f32x4*)(out + off + 4));
;                     sq += (x0[0] * x0[0] + x0[1] * x0[1]) + (x0[2] * x0[2] + x0[3] * x0[3]) + (x1[0] * x1[0] + x1[1] * x1[1]) + (x1[2] * x1[2] + x1[3] * x1[3]);
;                     if (xb) { u32x4 w; w.x = cvt_pk_bf16(x0[0], x0[1]); w.y = cvt_pk_bf16(x0[2], x0[3]); w.z = cvt_pk_bf16(x1[0], x1[1]); w.w = cvt_pk_bf16(x1[2], x1[3]); *(u32x4*)(xb + off) = w; }
;                 }
;                 sq += __shfl_xor(sq, 16); sq += __shfl_xor(sq, 32);
;                 if (fq == 0) unsafeAtomicAdd(ss + row, sq);
.LBB0_299:
	s_and_b64 vcc, exec, s[46:47]
	s_cbranch_vccz .Lg2_epi_old
	v_lshl_add_u32 v146, s31, 8, v154
	v_lshl_or_b32 v144, s33, 8, v156
	v_lshl_add_u32 v145, v146, 10, v144
	v_lshlrev_b32_e32 v144, 2, v145
	v_lshlrev_b32_e32 v145, 1, v145
	v_lshlrev_b32_e32 v146, 2, v146
	v_xor_b32_e32 v147, 16, v162
	v_lshlrev_b32_e32 v147, 2, v147
	v_xor_b32_e32 v148, 32, v162
	v_lshlrev_b32_e32 v148, 2, v148
	s_mov_b64 s[72:73], s[52:53]
	global_load_dwordx4 v[180:183], v144, s[72:73] nt
	global_load_dwordx4 v[184:187], v144, s[72:73] offset:16 nt
	global_load_dwordx4 v[188:191], v144, s[72:73] offset:512 nt
	global_load_dwordx4 v[192:195], v144, s[72:73] offset:528 nt
	s_add_u32 s72, s52, 0x10000
	s_addc_u32 s73, s53, 0
	global_load_dwordx4 v[196:199], v144, s[72:73] nt
	global_load_dwordx4 v[200:203], v144, s[72:73] offset:16 nt
	global_load_dwordx4 v[204:207], v144, s[72:73] offset:512 nt
	global_load_dwordx4 v[208:211], v144, s[72:73] offset:528 nt
	s_waitcnt vmcnt(4)
	v_fma_f32 v124, v124, 0.5, v180
	v_fma_f32 v125, v125, 0.5, v181
	v_fma_f32 v126, v126, 0.5, v182
	v_fma_f32 v127, v127, 0.5, v183
	v_fma_f32 v120, v120, 0.5, v184
	v_fma_f32 v121, v121, 0.5, v185
	v_fma_f32 v122, v122, 0.5, v186
	v_fma_f32 v123, v123, 0.5, v187
	v_fma_f32 v116, v116, 0.5, v188
	v_fma_f32 v117, v117, 0.5, v189
	v_fma_f32 v118, v118, 0.5, v190
	v_fma_f32 v119, v119, 0.5, v191
	v_fma_f32 v112, v112, 0.5, v192
	v_fma_f32 v113, v113, 0.5, v193
	v_fma_f32 v114, v114, 0.5, v194
	v_fma_f32 v115, v115, 0.5, v195
	s_add_u32 s72, s52, 0x20000
	s_addc_u32 s73, s53, 0
	global_load_dwordx4 v[212:215], v144, s[72:73] nt
	global_load_dwordx4 v[216:219], v144, s[72:73] offset:16 nt
	global_load_dwordx4 v[220:223], v144, s[72:73] offset:512 nt
	global_load_dwordx4 v[224:227], v144, s[72:73] offset:528 nt
	s_mov_b64 s[74:75], s[90:91]
	global_store_dwordx4 v144, v[124:127], s[74:75] nt
	global_store_dwordx4 v144, v[120:123], s[74:75] offset:16 nt
	global_store_dwordx4 v144, v[116:119], s[74:75] offset:512 nt
	global_store_dwordx4 v144, v[112:115], s[74:75] offset:528 nt
	v_cvt_pk_bf16_f32 v232, v124, v125
	v_cvt_pk_bf16_f32 v233, v126, v127
	v_cvt_pk_bf16_f32 v234, v120, v121
	v_cvt_pk_bf16_f32 v235, v122, v123
	v_cvt_pk_bf16_f32 v236, v116, v117
	v_cvt_pk_bf16_f32 v237, v118, v119
	v_cvt_pk_bf16_f32 v238, v112, v113
	v_cvt_pk_bf16_f32 v239, v114, v115
	s_mov_b64 s[82:83], s[70:71]
	global_store_dwordx4 v145, v[232:235], s[82:83]
	global_store_dwordx4 v145, v[236:239], s[82:83] offset:256
	v_mul_f32_e32 v228, v125, v125
	v_fmac_f32_e32 v228, v124, v124
	v_mul_f32_e32 v229, v121, v121
	v_fmac_f32_e32 v229, v120, v120
	v_mul_f32_e32 v230, v117, v117
	v_fmac_f32_e32 v230, v116, v116
	v_mul_f32_e32 v231, v113, v113
	v_fmac_f32_e32 v231, v112, v112
	v_mul_f32_e32 v240, v127, v127
	v_fmac_f32_e32 v240, v126, v126
	v_mul_f32_e32 v241, v123, v123
	v_fmac_f32_e32 v241, v122, v122
	v_mul_f32_e32 v242, v119, v119
	v_fmac_f32_e32 v242, v118, v118
	v_mul_f32_e32 v243, v115, v115
	v_fmac_f32_e32 v243, v114, v114
	v_add_f32_e32 v228, v228, v240
	v_add_f32_e32 v229, v229, v241
	v_add_f32_e32 v230, v230, v242
	v_add_f32_e32 v231, v231, v243
	v_add_f32_e32 v228, v228, v229
	v_add_f32_e32 v230, v230, v231
	v_add_f32_e32 v228, v228, v230
	ds_bpermute_b32 v229, v147, v228
	s_waitcnt lgkmcnt(0)
	v_add_f32_e32 v228, v228, v229
	ds_bpermute_b32 v229, v148, v228
	s_waitcnt lgkmcnt(0)
	v_add_f32_e32 v228, v228, v229
	s_and_saveexec_b64 s[6:7], s[8:9]
	s_nop 1
	global_atomic_add_f32 v146, v228, s[44:45]
	s_mov_b64 exec, s[6:7]
	s_waitcnt vmcnt(11)
	v_fma_f32 v108, v108, 0.5, v196
	v_fma_f32 v109, v109, 0.5, v197
	v_fma_f32 v110, v110, 0.5, v198
	v_fma_f32 v111, v111, 0.5, v199
	v_fma_f32 v104, v104, 0.5, v200
	v_fma_f32 v105, v105, 0.5, v201
	v_fma_f32 v106, v106, 0.5, v202
	v_fma_f32 v107, v107, 0.5, v203
	v_fma_f32 v100, v100, 0.5, v204
	v_fma_f32 v101, v101, 0.5, v205
	v_fma_f32 v102, v102, 0.5, v206
	v_fma_f32 v103, v103, 0.5, v207
	v_fma_f32 v96, v96, 0.5, v208
	v_fma_f32 v97, v97, 0.5, v209
	v_fma_f32 v98, v98, 0.5, v210
	v_fma_f32 v99, v99, 0.5, v211
	s_add_u32 s72, s52, 0x30000
	s_addc_u32 s73, s53, 0
	global_load_dwordx4 v[180:183], v144, s[72:73] nt
	global_load_dwordx4 v[184:187], v144, s[72:73] offset:16 nt
	global_load_dwordx4 v[188:191], v144, s[72:73] offset:512 nt
	global_load_dwordx4 v[192:195], v144, s[72:73] offset:528 nt
	s_add_u32 s74, s90, 0x10000
	s_addc_u32 s75, s91, 0
	global_store_dwordx4 v144, v[108:111], s[74:75] nt
	global_store_dwordx4 v144, v[104:107], s[74:75] offset:16 nt
	global_store_dwordx4 v144, v[100:103], s[74:75] offset:512 nt
	global_store_dwordx4 v144, v[96:99], s[74:75] offset:528 nt
	v_cvt_pk_bf16_f32 v232, v108, v109
	v_cvt_pk_bf16_f32 v233, v110, v111
	v_cvt_pk_bf16_f32 v234, v104, v105
	v_cvt_pk_bf16_f32 v235, v106, v107
	v_cvt_pk_bf16_f32 v236, v100, v101
	v_cvt_pk_bf16_f32 v237, v102, v103
	v_cvt_pk_bf16_f32 v238, v96, v97
	v_cvt_pk_bf16_f32 v239, v98, v99
	s_add_u32 s82, s70, 0x8000
	s_addc_u32 s83, s71, 0
	global_store_dwordx4 v145, v[232:235], s[82:83]
	global_store_dwordx4 v145, v[236:239], s[82:83] offset:256
	v_mul_f32_e32 v228, v109, v109
	v_fmac_f32_e32 v228, v108, v108
	v_mul_f32_e32 v229, v105, v105
	v_fmac_f32_e32 v229, v104, v104
	v_mul_f32_e32 v230, v101, v101
	v_fmac_f32_e32 v230, v100, v100
	v_mul_f32_e32 v231, v97, v97
	v_fmac_f32_e32 v231, v96, v96
	v_mul_f32_e32 v240, v111, v111
	v_fmac_f32_e32 v240, v110, v110
	v_mul_f32_e32 v241, v107, v107
	v_fmac_f32_e32 v241, v106, v106
	v_mul_f32_e32 v242, v103, v103
	v_fmac_f32_e32 v242, v102, v102
	v_mul_f32_e32 v243, v99, v99
	v_fmac_f32_e32 v243, v98, v98
	v_add_f32_e32 v228, v228, v240
	v_add_f32_e32 v229, v229, v241
	v_add_f32_e32 v230, v230, v242
	v_add_f32_e32 v231, v231, v243
	v_add_f32_e32 v228, v228, v229
	v_add_f32_e32 v230, v230, v231
	v_add_f32_e32 v228, v228, v230
	ds_bpermute_b32 v229, v147, v228
	s_waitcnt lgkmcnt(0)
; __device__ __forceinline__ unsigned cvt_pk_bf16(float lo, float hi) { f32x2_t v = {lo, hi}; bf16x2_t b = __builtin_convertvector(v, bf16x2_t); return __builtin_bit_cast(unsigned, b); }
;     __device__ __forceinline__ void operator()(const Acc& acc, const Unit& u, int wr, int wc, int fr, int fq) const {
;     ...
;                 const int row = row0 + ai * HALF + m * 16; float sq = 0.f;
; #pragma unroll
;                 for (int bj = 0; bj < 2; ++bj) {
;                     const size_t off = (size_t)row * DM + col0 + bj * HALF;
;                     const f32x4 b0 = *(const f32x4*)(base + off), b1 = *(const f32x4*)(base + off + 4);
;                     const f32x4 x0 = b0 + acc[ai][bj][m][0] * alpha, x1 = b1 + acc[ai][bj][m][1] * alpha;
;                     __builtin_nontemporal_store(x0, (f32x4*)(out + off)); __builtin_nontemporal_store(x1, (f32x4*)(out + off + 4));
;                     sq += (x0[0] * x0[0] + x0[1] * x0[1]) + (x0[2] * x0[2] + x0[3] * x0[3]) + (x1[0] * x1[0] + x1[1] * x1[1]) + (x1[2] * x1[2] + x1[3] * x1[3]);
;                     if (xb) { u32x4 w; w.x = cvt_pk_bf16(x0[0], x0[1]); w.y = cvt_pk_bf16(x0[2], x0[3]); w.z = cvt_pk_bf16(x1[0], x1[1]); w.w = cvt_pk_bf16(x1[2], x1[3]); *(u32x4*)(xb + off) = w; }
;                 }
;                 sq += __shfl_xor(sq, 16); sq += __shfl_xor(sq, 32);
;                 if (fq == 0) unsafeAtomicAdd(ss + row, sq);
	v_add_f32_e32 v228, v228, v229
	ds_bpermute_b32 v229, v148, v228
	s_waitcnt lgkmcnt(0)
	v_add_f32_e32 v228, v228, v229
	s_and_saveexec_b64 s[6:7], s[8:9]
	s_nop 1
	global_atomic_add_f32 v146, v228, s[44:45] offset:64
	s_mov_b64 exec, s[6:7]
	s_waitcnt vmcnt(18)
	v_fma_f32 v92, v92, 0.5, v212
	v_fma_f32 v93, v93, 0.5, v213
	v_fma_f32 v94, v94, 0.5, v214
	v_fma_f32 v95, v95, 0.5, v215
	v_fma_f32 v88, v88, 0.5, v216
	v_fma_f32 v89, v89, 0.5, v217
	v_fma_f32 v90, v90, 0.5, v218
	v_fma_f32 v91, v91, 0.5, v219
	v_fma_f32 v84, v84, 0.5, v220
	v_fma_f32 v85, v85, 0.5, v221
	v_fma_f32 v86, v86, 0.5, v222
	v_fma_f32 v87, v87, 0.5, v223
	v_fma_f32 v80, v80, 0.5, v224
	v_fma_f32 v81, v81, 0.5, v225
	v_fma_f32 v82, v82, 0.5, v226
	v_fma_f32 v83, v83, 0.5, v227
	s_add_u32 s72, s52, 0x80000
	s_addc_u32 s73, s53, 0
	global_load_dwordx4 v[196:199], v144, s[72:73] nt
	global_load_dwordx4 v[200:203], v144, s[72:73] offset:16 nt
	global_load_dwordx4 v[204:207], v144, s[72:73] offset:512 nt
	global_load_dwordx4 v[208:211], v144, s[72:73] offset:528 nt
	s_add_u32 s74, s90, 0x20000
	s_addc_u32 s75, s91, 0
	global_store_dwordx4 v144, v[92:95], s[74:75] nt
	global_store_dwordx4 v144, v[88:91], s[74:75] offset:16 nt
	global_store_dwordx4 v144, v[84:87], s[74:75] offset:512 nt
	global_store_dwordx4 v144, v[80:83], s[74:75] offset:528 nt
	v_cvt_pk_bf16_f32 v232, v92, v93
	v_cvt_pk_bf16_f32 v233, v94, v95
	v_cvt_pk_bf16_f32 v234, v88, v89
	v_cvt_pk_bf16_f32 v235, v90, v91
	v_cvt_pk_bf16_f32 v236, v84, v85
	v_cvt_pk_bf16_f32 v237, v86, v87
	v_cvt_pk_bf16_f32 v238, v80, v81
	v_cvt_pk_bf16_f32 v239, v82, v83
	s_add_u32 s82, s70, 0x10000
	s_addc_u32 s83, s71, 0
	global_store_dwordx4 v145, v[232:235], s[82:83]
	global_store_dwordx4 v145, v[236:239], s[82:83] offset:256
	v_mul_f32_e32 v228, v93, v93
	v_fmac_f32_e32 v228, v92, v92
	v_mul_f32_e32 v229, v89, v89
	v_fmac_f32_e32 v229, v88, v88
	v_mul_f32_e32 v230, v85, v85
	v_fmac_f32_e32 v230, v84, v84
	v_mul_f32_e32 v231, v81, v81
	v_fmac_f32_e32 v231, v80, v80
	v_mul_f32_e32 v240, v95, v95
	v_fmac_f32_e32 v240, v94, v94
	v_mul_f32_e32 v241, v91, v91
	v_fmac_f32_e32 v241, v90, v90
	v_mul_f32_e32 v242, v87, v87
	v_fmac_f32_e32 v242, v86, v86
	v_mul_f32_e32 v243, v83, v83
	v_fmac_f32_e32 v243, v82, v82
	v_add_f32_e32 v228, v228, v240
	v_add_f32_e32 v229, v229, v241
	v_add_f32_e32 v230, v230, v242
	v_add_f32_e32 v231, v231, v243
	v_add_f32_e32 v228, v228, v229
	v_add_f32_e32 v230, v230, v231
	v_add_f32_e32 v228, v228, v230
	ds_bpermute_b32 v229, v147, v228
	s_waitcnt lgkmcnt(0)
	v_add_f32_e32 v228, v228, v229
	ds_bpermute_b32 v229, v148, v228
	s_waitcnt lgkmcnt(0)
	v_add_f32_e32 v228, v228, v229
	s_and_saveexec_b64 s[6:7], s[8:9]
	s_nop 1
	global_atomic_add_f32 v146, v228, s[44:45] offset:128
	s_mov_b64 exec, s[6:7]
	s_waitcnt vmcnt(18)
	v_fma_f32 v76, v76, 0.5, v180
	v_fma_f32 v77, v77, 0.5, v181
	v_fma_f32 v78, v78, 0.5, v182
	v_fma_f32 v79, v79, 0.5, v183
	v_fma_f32 v72, v72, 0.5, v184
	v_fma_f32 v73, v73, 0.5, v185
	v_fma_f32 v74, v74, 0.5, v186
	v_fma_f32 v75, v75, 0.5, v187
	v_fma_f32 v68, v68, 0.5, v188
	v_fma_f32 v69, v69, 0.5, v189
	v_fma_f32 v70, v70, 0.5, v190
	v_fma_f32 v71, v71, 0.5, v191
	v_fma_f32 v64, v64, 0.5, v192
	v_fma_f32 v65, v65, 0.5, v193
	v_fma_f32 v66, v66, 0.5, v194
	v_fma_f32 v67, v67, 0.5, v195
	s_add_u32 s72, s52, 0x90000
	s_addc_u32 s73, s53, 0
	global_load_dwordx4 v[212:215], v144, s[72:73] nt
	global_load_dwordx4 v[216:219], v144, s[72:73] offset:16 nt
	global_load_dwordx4 v[220:223], v144, s[72:73] offset:512 nt
	global_load_dwordx4 v[224:227], v144, s[72:73] offset:528 nt
	s_add_u32 s74, s90, 0x30000
	s_addc_u32 s75, s91, 0
	global_store_dwordx4 v144, v[76:79], s[74:75] nt
	global_store_dwordx4 v144, v[72:75], s[74:75] offset:16 nt
	global_store_dwordx4 v144, v[68:71], s[74:75] offset:512 nt
	global_store_dwordx4 v144, v[64:67], s[74:75] offset:528 nt
	v_cvt_pk_bf16_f32 v232, v76, v77
	v_cvt_pk_bf16_f32 v233, v78, v79
	v_cvt_pk_bf16_f32 v234, v72, v73
	v_cvt_pk_bf16_f32 v235, v74, v75
	v_cvt_pk_bf16_f32 v236, v68, v69
	v_cvt_pk_bf16_f32 v237, v70, v71
	v_cvt_pk_bf16_f32 v238, v64, v65
	v_cvt_pk_bf16_f32 v239, v66, v67
	s_add_u32 s82, s70, 0x18000
	s_addc_u32 s83, s71, 0
	global_store_dwordx4 v145, v[232:235], s[82:83]
	global_store_dwordx4 v145, v[236:239], s[82:83] offset:256
	v_mul_f32_e32 v228, v77, v77
	v_fmac_f32_e32 v228, v76, v76
	v_mul_f32_e32 v229, v73, v73
	v_fmac_f32_e32 v229, v72, v72
	v_mul_f32_e32 v230, v69, v69
	v_fmac_f32_e32 v230, v68, v68
	v_mul_f32_e32 v231, v65, v65
	v_fmac_f32_e32 v231, v64, v64
	v_mul_f32_e32 v240, v79, v79
	v_fmac_f32_e32 v240, v78, v78
	v_mul_f32_e32 v241, v75, v75
	v_fmac_f32_e32 v241, v74, v74
	v_mul_f32_e32 v242, v71, v71
	v_fmac_f32_e32 v242, v70, v70
	v_mul_f32_e32 v243, v67, v67
	v_fmac_f32_e32 v243, v66, v66
	v_add_f32_e32 v228, v228, v240
	v_add_f32_e32 v229, v229, v241
	v_add_f32_e32 v230, v230, v242
	v_add_f32_e32 v231, v231, v243
	v_add_f32_e32 v228, v228, v229
	v_add_f32_e32 v230, v230, v231
	v_add_f32_e32 v228, v228, v230
	ds_bpermute_b32 v229, v147, v228
	s_waitcnt lgkmcnt(0)
	v_add_f32_e32 v228, v228, v229
	ds_bpermute_b32 v229, v148, v228
	s_waitcnt lgkmcnt(0)
	v_add_f32_e32 v228, v228, v229
	s_and_saveexec_b64 s[6:7], s[8:9]
	s_nop 1
	global_atomic_add_f32 v146, v228, s[44:45] offset:192
	s_mov_b64 exec, s[6:7]
	s_waitcnt vmcnt(18)
; __device__ __forceinline__ unsigned cvt_pk_bf16(float lo, float hi) { f32x2_t v = {lo, hi}; bf16x2_t b = __builtin_convertvector(v, bf16x2_t); return __builtin_bit_cast(unsigned, b); }
;     __device__ __forceinline__ void operator()(const Acc& acc, const Unit& u, int wr, int wc, int fr, int fq) const {
;     ...
;                 const int row = row0 + ai * HALF + m * 16; float sq = 0.f;
; #pragma unroll
;                 for (int bj = 0; bj < 2; ++bj) {
;                     const size_t off = (size_t)row * DM + col0 + bj * HALF;
;                     const f32x4 b0 = *(const f32x4*)(base + off), b1 = *(const f32x4*)(base + off + 4);
;                     const f32x4 x0 = b0 + acc[ai][bj][m][0] * alpha, x1 = b1 + acc[ai][bj][m][1] * alpha;
;                     __builtin_nontemporal_store(x0, (f32x4*)(out + off)); __builtin_nontemporal_store(x1, (f32x4*)(out + off + 4));
;                     sq += (x0[0] * x0[0] + x0[1] * x0[1]) + (x0[2] * x0[2] + x0[3] * x0[3]) + (x1[0] * x1[0] + x1[1] * x1[1]) + (x1[2] * x1[2] + x1[3] * x1[3]);
;                     if (xb) { u32x4 w; w.x = cvt_pk_bf16(x0[0], x0[1]); w.y = cvt_pk_bf16(x0[2], x0[3]); w.z = cvt_pk_bf16(x1[0], x1[1]); w.w = cvt_pk_bf16(x1[2], x1[3]); *(u32x4*)(xb + off) = w; }
;                 }
;                 sq += __shfl_xor(sq, 16); sq += __shfl_xor(sq, 32);
;                 if (fq == 0) unsafeAtomicAdd(ss + row, sq);
	v_fma_f32 v60, v60, 0.5, v196
	v_fma_f32 v61, v61, 0.5, v197
	v_fma_f32 v62, v62, 0.5, v198
	v_fma_f32 v63, v63, 0.5, v199
	v_fma_f32 v56, v56, 0.5, v200
	v_fma_f32 v57, v57, 0.5, v201
	v_fma_f32 v58, v58, 0.5, v202
	v_fma_f32 v59, v59, 0.5, v203
	v_fma_f32 v52, v52, 0.5, v204
	v_fma_f32 v53, v53, 0.5, v205
	v_fma_f32 v54, v54, 0.5, v206
	v_fma_f32 v55, v55, 0.5, v207
	v_fma_f32 v48, v48, 0.5, v208
	v_fma_f32 v49, v49, 0.5, v209
	v_fma_f32 v50, v50, 0.5, v210
	v_fma_f32 v51, v51, 0.5, v211
	s_add_u32 s72, s52, 0xa0000
	s_addc_u32 s73, s53, 0
	global_load_dwordx4 v[180:183], v144, s[72:73] nt
	global_load_dwordx4 v[184:187], v144, s[72:73] offset:16 nt
	global_load_dwordx4 v[188:191], v144, s[72:73] offset:512 nt
	global_load_dwordx4 v[192:195], v144, s[72:73] offset:528 nt
	s_add_u32 s74, s90, 0x80000
	s_addc_u32 s75, s91, 0
	global_store_dwordx4 v144, v[60:63], s[74:75] nt
	global_store_dwordx4 v144, v[56:59], s[74:75] offset:16 nt
	global_store_dwordx4 v144, v[52:55], s[74:75] offset:512 nt
	global_store_dwordx4 v144, v[48:51], s[74:75] offset:528 nt
	v_cvt_pk_bf16_f32 v232, v60, v61
	v_cvt_pk_bf16_f32 v233, v62, v63
	v_cvt_pk_bf16_f32 v234, v56, v57
	v_cvt_pk_bf16_f32 v235, v58, v59
	v_cvt_pk_bf16_f32 v236, v52, v53
	v_cvt_pk_bf16_f32 v237, v54, v55
	v_cvt_pk_bf16_f32 v238, v48, v49
	v_cvt_pk_bf16_f32 v239, v50, v51
	s_add_u32 s82, s70, 0x40000
	s_addc_u32 s83, s71, 0
	global_store_dwordx4 v145, v[232:235], s[82:83]
	global_store_dwordx4 v145, v[236:239], s[82:83] offset:256
	v_mul_f32_e32 v228, v61, v61
	v_fmac_f32_e32 v228, v60, v60
	v_mul_f32_e32 v229, v57, v57
	v_fmac_f32_e32 v229, v56, v56
	v_mul_f32_e32 v230, v53, v53
	v_fmac_f32_e32 v230, v52, v52
	v_mul_f32_e32 v231, v49, v49
	v_fmac_f32_e32 v231, v48, v48
	v_mul_f32_e32 v240, v63, v63
	v_fmac_f32_e32 v240, v62, v62
	v_mul_f32_e32 v241, v59, v59
	v_fmac_f32_e32 v241, v58, v58
	v_mul_f32_e32 v242, v55, v55
	v_fmac_f32_e32 v242, v54, v54
	v_mul_f32_e32 v243, v51, v51
	v_fmac_f32_e32 v243, v50, v50
	v_add_f32_e32 v228, v228, v240
	v_add_f32_e32 v229, v229, v241
	v_add_f32_e32 v230, v230, v242
	v_add_f32_e32 v231, v231, v243
	v_add_f32_e32 v228, v228, v229
	v_add_f32_e32 v230, v230, v231
	v_add_f32_e32 v228, v228, v230
	ds_bpermute_b32 v229, v147, v228
	s_waitcnt lgkmcnt(0)
	v_add_f32_e32 v228, v228, v229
	ds_bpermute_b32 v229, v148, v228
	s_waitcnt lgkmcnt(0)
	v_add_f32_e32 v228, v228, v229
	s_and_saveexec_b64 s[6:7], s[8:9]
	s_nop 1
	global_atomic_add_f32 v146, v228, s[44:45] offset:512
	s_mov_b64 exec, s[6:7]
	s_waitcnt vmcnt(18)
	v_fma_f32 v44, v44, 0.5, v212
	v_fma_f32 v45, v45, 0.5, v213
	v_fma_f32 v46, v46, 0.5, v214
	v_fma_f32 v47, v47, 0.5, v215
	v_fma_f32 v40, v40, 0.5, v216
	v_fma_f32 v41, v41, 0.5, v217
	v_fma_f32 v42, v42, 0.5, v218
	v_fma_f32 v43, v43, 0.5, v219
	v_fma_f32 v36, v36, 0.5, v220
	v_fma_f32 v37, v37, 0.5, v221
	v_fma_f32 v38, v38, 0.5, v222
	v_fma_f32 v39, v39, 0.5, v223
	v_fma_f32 v32, v32, 0.5, v224
	v_fma_f32 v33, v33, 0.5, v225
	v_fma_f32 v34, v34, 0.5, v226
	v_fma_f32 v35, v35, 0.5, v227
	s_add_u32 s72, s52, 0xb0000
	s_addc_u32 s73, s53, 0
	global_load_dwordx4 v[196:199], v144, s[72:73] nt
	global_load_dwordx4 v[200:203], v144, s[72:73] offset:16 nt
	global_load_dwordx4 v[204:207], v144, s[72:73] offset:512 nt
	global_load_dwordx4 v[208:211], v144, s[72:73] offset:528 nt
	s_add_u32 s74, s90, 0x90000
	s_addc_u32 s75, s91, 0
	global_store_dwordx4 v144, v[44:47], s[74:75] nt
	global_store_dwordx4 v144, v[40:43], s[74:75] offset:16 nt
	global_store_dwordx4 v144, v[36:39], s[74:75] offset:512 nt
	global_store_dwordx4 v144, v[32:35], s[74:75] offset:528 nt
	v_cvt_pk_bf16_f32 v232, v44, v45
	v_cvt_pk_bf16_f32 v233, v46, v47
	v_cvt_pk_bf16_f32 v234, v40, v41
	v_cvt_pk_bf16_f32 v235, v42, v43
	v_cvt_pk_bf16_f32 v236, v36, v37
	v_cvt_pk_bf16_f32 v237, v38, v39
	v_cvt_pk_bf16_f32 v238, v32, v33
	v_cvt_pk_bf16_f32 v239, v34, v35
	s_add_u32 s82, s70, 0x48000
	s_addc_u32 s83, s71, 0
	global_store_dwordx4 v145, v[232:235], s[82:83]
	global_store_dwordx4 v145, v[236:239], s[82:83] offset:256
	v_mul_f32_e32 v228, v45, v45
	v_fmac_f32_e32 v228, v44, v44
	v_mul_f32_e32 v229, v41, v41
	v_fmac_f32_e32 v229, v40, v40
	v_mul_f32_e32 v230, v37, v37
	v_fmac_f32_e32 v230, v36, v36
	v_mul_f32_e32 v231, v33, v33
	v_fmac_f32_e32 v231, v32, v32
	v_mul_f32_e32 v240, v47, v47
	v_fmac_f32_e32 v240, v46, v46
	v_mul_f32_e32 v241, v43, v43
	v_fmac_f32_e32 v241, v42, v42
	v_mul_f32_e32 v242, v39, v39
	v_fmac_f32_e32 v242, v38, v38
	v_mul_f32_e32 v243, v35, v35
	v_fmac_f32_e32 v243, v34, v34
	v_add_f32_e32 v228, v228, v240
	v_add_f32_e32 v229, v229, v241
	v_add_f32_e32 v230, v230, v242
	v_add_f32_e32 v231, v231, v243
	v_add_f32_e32 v228, v228, v229
	v_add_f32_e32 v230, v230, v231
	v_add_f32_e32 v228, v228, v230
	ds_bpermute_b32 v229, v147, v228
	s_waitcnt lgkmcnt(0)
; __device__ __forceinline__ unsigned cvt_pk_bf16(float lo, float hi) { f32x2_t v = {lo, hi}; bf16x2_t b = __builtin_convertvector(v, bf16x2_t); return __builtin_bit_cast(unsigned, b); }
;     __device__ __forceinline__ void operator()(const Acc& acc, const Unit& u, int wr, int wc, int fr, int fq) const {
;     ...
;                 const int row = row0 + ai * HALF + m * 16; float sq = 0.f;
; #pragma unroll
;                 for (int bj = 0; bj < 2; ++bj) {
;                     const size_t off = (size_t)row * DM + col0 + bj * HALF;
;                     const f32x4 b0 = *(const f32x4*)(base + off), b1 = *(const f32x4*)(base + off + 4);
;                     const f32x4 x0 = b0 + acc[ai][bj][m][0] * alpha, x1 = b1 + acc[ai][bj][m][1] * alpha;
;                     __builtin_nontemporal_store(x0, (f32x4*)(out + off)); __builtin_nontemporal_store(x1, (f32x4*)(out + off + 4));
;                     sq += (x0[0] * x0[0] + x0[1] * x0[1]) + (x0[2] * x0[2] + x0[3] * x0[3]) + (x1[0] * x1[0] + x1[1] * x1[1]) + (x1[2] * x1[2] + x1[3] * x1[3]);
;                     if (xb) { u32x4 w; w.x = cvt_pk_bf16(x0[0], x0[1]); w.y = cvt_pk_bf16(x0[2], x0[3]); w.z = cvt_pk_bf16(x1[0], x1[1]); w.w = cvt_pk_bf16(x1[2], x1[3]); *(u32x4*)(xb + off) = w; }
;                 }
;                 sq += __shfl_xor(sq, 16); sq += __shfl_xor(sq, 32);
;                 if (fq == 0) unsafeAtomicAdd(ss + row, sq);
	v_add_f32_e32 v228, v228, v229
	ds_bpermute_b32 v229, v148, v228
	s_waitcnt lgkmcnt(0)
	v_add_f32_e32 v228, v228, v229
	s_and_saveexec_b64 s[6:7], s[8:9]
	s_nop 1
	global_atomic_add_f32 v146, v228, s[44:45] offset:576
	s_mov_b64 exec, s[6:7]
	s_waitcnt vmcnt(18)
	v_fma_f32 v28, v28, 0.5, v180
	v_fma_f32 v29, v29, 0.5, v181
	v_fma_f32 v30, v30, 0.5, v182
	v_fma_f32 v31, v31, 0.5, v183
	v_fma_f32 v24, v24, 0.5, v184
	v_fma_f32 v25, v25, 0.5, v185
	v_fma_f32 v26, v26, 0.5, v186
	v_fma_f32 v27, v27, 0.5, v187
	v_fma_f32 v20, v20, 0.5, v188
	v_fma_f32 v21, v21, 0.5, v189
	v_fma_f32 v22, v22, 0.5, v190
	v_fma_f32 v23, v23, 0.5, v191
	v_fma_f32 v16, v16, 0.5, v192
	v_fma_f32 v17, v17, 0.5, v193
	v_fma_f32 v18, v18, 0.5, v194
	v_fma_f32 v19, v19, 0.5, v195
	s_add_u32 s74, s90, 0xa0000
	s_addc_u32 s75, s91, 0
	global_store_dwordx4 v144, v[28:31], s[74:75] nt
	global_store_dwordx4 v144, v[24:27], s[74:75] offset:16 nt
	global_store_dwordx4 v144, v[20:23], s[74:75] offset:512 nt
	global_store_dwordx4 v144, v[16:19], s[74:75] offset:528 nt
	v_cvt_pk_bf16_f32 v232, v28, v29
	v_cvt_pk_bf16_f32 v233, v30, v31
	v_cvt_pk_bf16_f32 v234, v24, v25
	v_cvt_pk_bf16_f32 v235, v26, v27
	v_cvt_pk_bf16_f32 v236, v20, v21
	v_cvt_pk_bf16_f32 v237, v22, v23
	v_cvt_pk_bf16_f32 v238, v16, v17
	v_cvt_pk_bf16_f32 v239, v18, v19
	s_add_u32 s82, s70, 0x50000
	s_addc_u32 s83, s71, 0
	global_store_dwordx4 v145, v[232:235], s[82:83]
	global_store_dwordx4 v145, v[236:239], s[82:83] offset:256
	v_mul_f32_e32 v228, v29, v29
	v_fmac_f32_e32 v228, v28, v28
	v_mul_f32_e32 v229, v25, v25
	v_fmac_f32_e32 v229, v24, v24
	v_mul_f32_e32 v230, v21, v21
	v_fmac_f32_e32 v230, v20, v20
	v_mul_f32_e32 v231, v17, v17
	v_fmac_f32_e32 v231, v16, v16
	v_mul_f32_e32 v240, v31, v31
	v_fmac_f32_e32 v240, v30, v30
	v_mul_f32_e32 v241, v27, v27
	v_fmac_f32_e32 v241, v26, v26
	v_mul_f32_e32 v242, v23, v23
	v_fmac_f32_e32 v242, v22, v22
	v_mul_f32_e32 v243, v19, v19
	v_fmac_f32_e32 v243, v18, v18
	v_add_f32_e32 v228, v228, v240
	v_add_f32_e32 v229, v229, v241
	v_add_f32_e32 v230, v230, v242
	v_add_f32_e32 v231, v231, v243
	v_add_f32_e32 v228, v228, v229
	v_add_f32_e32 v230, v230, v231
	v_add_f32_e32 v228, v228, v230
	ds_bpermute_b32 v229, v147, v228
	s_waitcnt lgkmcnt(0)
	v_add_f32_e32 v228, v228, v229
	ds_bpermute_b32 v229, v148, v228
	s_waitcnt lgkmcnt(0)
	v_add_f32_e32 v228, v228, v229
	s_and_saveexec_b64 s[6:7], s[8:9]
	s_nop 1
	global_atomic_add_f32 v146, v228, s[44:45] offset:640
	s_mov_b64 exec, s[6:7]
	s_waitcnt vmcnt(14)
	v_fma_f32 v12, v12, 0.5, v196
	v_fma_f32 v13, v13, 0.5, v197
	v_fma_f32 v14, v14, 0.5, v198
	v_fma_f32 v15, v15, 0.5, v199
	v_fma_f32 v8, v8, 0.5, v200
	v_fma_f32 v9, v9, 0.5, v201
	v_fma_f32 v10, v10, 0.5, v202
	v_fma_f32 v11, v11, 0.5, v203
	v_fma_f32 v4, v4, 0.5, v204
	v_fma_f32 v5, v5, 0.5, v205
	v_fma_f32 v6, v6, 0.5, v206
	v_fma_f32 v7, v7, 0.5, v207
	v_fma_f32 v0, v0, 0.5, v208
	v_fma_f32 v1, v1, 0.5, v209
	v_fma_f32 v2, v2, 0.5, v210
	v_fma_f32 v3, v3, 0.5, v211
	s_add_u32 s74, s90, 0xb0000
	s_addc_u32 s75, s91, 0
	global_store_dwordx4 v144, v[12:15], s[74:75] nt
	global_store_dwordx4 v144, v[8:11], s[74:75] offset:16 nt
	global_store_dwordx4 v144, v[4:7], s[74:75] offset:512 nt
	global_store_dwordx4 v144, v[0:3], s[74:75] offset:528 nt
	v_cvt_pk_bf16_f32 v232, v12, v13
	v_cvt_pk_bf16_f32 v233, v14, v15
	v_cvt_pk_bf16_f32 v234, v8, v9
	v_cvt_pk_bf16_f32 v235, v10, v11
	v_cvt_pk_bf16_f32 v236, v4, v5
	v_cvt_pk_bf16_f32 v237, v6, v7
	v_cvt_pk_bf16_f32 v238, v0, v1
	v_cvt_pk_bf16_f32 v239, v2, v3
	s_add_u32 s82, s70, 0x58000
	s_addc_u32 s83, s71, 0
	global_store_dwordx4 v145, v[232:235], s[82:83]
	global_store_dwordx4 v145, v[236:239], s[82:83] offset:256
	v_mul_f32_e32 v228, v13, v13
	v_fmac_f32_e32 v228, v12, v12
	v_mul_f32_e32 v229, v9, v9
	v_fmac_f32_e32 v229, v8, v8
	v_mul_f32_e32 v230, v5, v5
	v_fmac_f32_e32 v230, v4, v4
	v_mul_f32_e32 v231, v1, v1
	v_fmac_f32_e32 v231, v0, v0
	v_mul_f32_e32 v240, v15, v15
	v_fmac_f32_e32 v240, v14, v14
	v_mul_f32_e32 v241, v11, v11
	v_fmac_f32_e32 v241, v10, v10
	v_mul_f32_e32 v242, v7, v7
	v_fmac_f32_e32 v242, v6, v6
	v_mul_f32_e32 v243, v3, v3
	v_fmac_f32_e32 v243, v2, v2
	v_add_f32_e32 v228, v228, v240
	v_add_f32_e32 v229, v229, v241
	v_add_f32_e32 v230, v230, v242
	v_add_f32_e32 v231, v231, v243
	v_add_f32_e32 v228, v228, v229
	v_add_f32_e32 v230, v230, v231
	v_add_f32_e32 v228, v228, v230
	ds_bpermute_b32 v229, v147, v228
	s_waitcnt lgkmcnt(0)
	v_add_f32_e32 v228, v228, v229
	ds_bpermute_b32 v229, v148, v228
	s_waitcnt lgkmcnt(0)
	v_add_f32_e32 v228, v228, v229
	s_and_saveexec_b64 s[6:7], s[8:9]
	s_nop 1
	global_atomic_add_f32 v146, v228, s[44:45] offset:704
	s_mov_b64 exec, s[6:7]
	s_branch .Lg2_epi_done

; __device__ __forceinline__ unsigned cvt_pk_bf16(float lo, float hi) { f32x2_t v = {lo, hi}; bf16x2_t b = __builtin_convertvector(v, bf16x2_t); return __builtin_bit_cast(unsigned, b); }
;     __device__ __forceinline__ void operator()(const Acc& acc, const Unit& u, int wr, int wc, int fr, int fq) const {
;     ...
;                     const size_t off = (size_t)row * DM + col0 + bj * HALF;
;                     const f32x4 b0 = *(const f32x4*)(base + off), b1 = *(const f32x4*)(base + off + 4);
;                     const f32x4 x0 = b0 + acc[ai][bj][m][0] * alpha, x1 = b1 + acc[ai][bj][m][1] * alpha;
;                     __builtin_nontemporal_store(x0, (f32x4*)(out + off)); __builtin_nontemporal_store(x1, (f32x4*)(out + off + 4));
;                     sq += (x0[0] * x0[0] + x0[1] * x0[1]) + (x0[2] * x0[2] + x0[3] * x0[3]) + (x1[0] * x1[0] + x1[1] * x1[1]) + (x1[2] * x1[2] + x1[3] * x1[3]);
;                     if (xb) { u32x4 w; w.x = cvt_pk_bf16(x0[0], x0[1]); w.y = cvt_pk_bf16(x0[2], x0[3]); w.z = cvt_pk_bf16(x1[0], x1[1]); w.w = cvt_pk_bf16(x1[2], x1[3]); *(u32x4*)(xb + off) = w; }
.LBB0_1237:
	v_lshl_add_u32 v146, s12, 8, v152
	v_lshl_or_b32 v144, s46, 8, v154
	v_ashrrev_i32_e32 v147, 31, v146
	v_ashrrev_i32_e32 v145, 31, v144
	v_lshlrev_b64 v[148:149], 10, v[146:147]
	v_lshl_add_u64 v[148:149], v[148:149], 0, v[144:145]
	v_lshl_add_u64 v[150:151], v[148:149], 2, s[82:83]
	global_load_dwordx4 v[162:165], v[150:151], off nt
	global_load_dwordx4 v[166:169], v[150:151], off offset:16 nt
	v_cndmask_b32_e64 v158, 0, 1, s[36:37]
	v_cmp_ne_u32_e64 s[12:13], 1, v158
	s_andn2_b64 vcc, exec, s[36:37]
	s_waitcnt vmcnt(0)
	v_pk_add_f32 v[126:127], v[126:127], v[164:165]
	v_pk_add_f32 v[124:125], v[124:125], v[162:163]
	v_pk_add_f32 v[122:123], v[122:123], v[168:169]
	v_pk_add_f32 v[120:121], v[120:121], v[166:167]
	global_store_dwordx4 v[150:151], v[124:127], off nt
	global_store_dwordx4 v[150:151], v[120:123], off offset:16 nt
	s_cbranch_vccnz .LBB0_1239
	v_cvt_pk_bf16_f32 v162, v124, v125
	v_cvt_pk_bf16_f32 v163, v126, v127
	v_cvt_pk_bf16_f32 v164, v120, v121
	v_cvt_pk_bf16_f32 v165, v122, v123
	v_lshl_add_u64 v[158:159], v[148:149], 1, s[72:73]
	global_store_dwordx4 v[158:159], v[162:165], off
.LBB0_1239:
	global_load_dwordx4 v[162:165], v[150:151], off offset:512 nt
	s_nop 0
	global_load_dwordx4 v[166:169], v[150:151], off offset:528 nt
	s_and_b64 vcc, exec, s[12:13]
	s_waitcnt vmcnt(1)
	v_pk_add_f32 v[118:119], v[118:119], v[164:165]
	v_pk_add_f32 v[116:117], v[116:117], v[162:163]
	s_waitcnt vmcnt(0)
	v_pk_add_f32 v[114:115], v[114:115], v[168:169]
	v_pk_add_f32 v[112:113], v[112:113], v[166:167]
	global_store_dwordx4 v[150:151], v[116:119], off offset:512 nt
	global_store_dwordx4 v[150:151], v[112:115], off offset:528 nt
	s_cbranch_vccnz .LBB0_1241
	v_lshlrev_b64 v[158:159], 1, v[148:149]
	v_or_b32_e32 v158, 0x100, v158
	v_cvt_pk_bf16_f32 v148, v116, v117
	v_cvt_pk_bf16_f32 v149, v118, v119
	v_cvt_pk_bf16_f32 v150, v112, v113
	v_cvt_pk_bf16_f32 v151, v114, v115
	v_lshl_add_u64 v[158:159], s[72:73], 0, v[158:159]
	global_store_dwordx4 v[158:159], v[148:151], off

; __device__ __forceinline__ unsigned cvt_pk_bf16(float lo, float hi) { f32x2_t v = {lo, hi}; bf16x2_t b = __builtin_convertvector(v, bf16x2_t); return __builtin_bit_cast(unsigned, b); }
;     __device__ __forceinline__ void operator()(const Acc& acc, const Unit& u, int wr, int wc, int fr, int fq) const {
;     ...
;                     const size_t off = (size_t)row * DM + col0 + bj * HALF;
;                     const f32x4 b0 = *(const f32x4*)(base + off), b1 = *(const f32x4*)(base + off + 4);
;                     const f32x4 x0 = b0 + acc[ai][bj][m][0] * alpha, x1 = b1 + acc[ai][bj][m][1] * alpha;
;                     __builtin_nontemporal_store(x0, (f32x4*)(out + off)); __builtin_nontemporal_store(x1, (f32x4*)(out + off + 4));
;                     sq += (x0[0] * x0[0] + x0[1] * x0[1]) + (x0[2] * x0[2] + x0[3] * x0[3]) + (x1[0] * x1[0] + x1[1] * x1[1]) + (x1[2] * x1[2] + x1[3] * x1[3]);
;                     if (xb) { u32x4 w; w.x = cvt_pk_bf16(x0[0], x0[1]); w.y = cvt_pk_bf16(x0[2], x0[3]); w.z = cvt_pk_bf16(x1[0], x1[1]); w.w = cvt_pk_bf16(x1[2], x1[3]); *(u32x4*)(xb + off) = w; }
.LBB0_1243:
	s_or_b64 exec, exec, s[6:7]
	v_or_b32_e32 v112, 16, v146
	s_waitcnt lgkmcnt(0)
	v_ashrrev_i32_e32 v113, 31, v112
	v_lshlrev_b64 v[114:115], 10, v[112:113]
	v_lshl_add_u64 v[114:115], v[114:115], 0, v[144:145]
	v_lshl_add_u64 v[116:117], v[114:115], 2, s[82:83]
	global_load_dwordx4 v[118:121], v[116:117], off nt
	global_load_dwordx4 v[122:125], v[116:117], off offset:16 nt
	s_and_b64 vcc, exec, s[12:13]
	s_waitcnt vmcnt(1)
	v_pk_add_f32 v[110:111], v[110:111], v[120:121]
	v_pk_add_f32 v[108:109], v[108:109], v[118:119]
	s_waitcnt vmcnt(0)
	v_pk_add_f32 v[106:107], v[106:107], v[124:125]
	v_pk_add_f32 v[104:105], v[104:105], v[122:123]
	global_store_dwordx4 v[116:117], v[108:111], off nt
	global_store_dwordx4 v[116:117], v[104:107], off offset:16 nt
	s_cbranch_vccnz .LBB0_1245
	v_cvt_pk_bf16_f32 v118, v108, v109
	v_cvt_pk_bf16_f32 v119, v110, v111
	v_cvt_pk_bf16_f32 v120, v104, v105
	v_cvt_pk_bf16_f32 v121, v106, v107
	v_lshl_add_u64 v[122:123], v[114:115], 1, s[72:73]
	global_store_dwordx4 v[122:123], v[118:121], off
.LBB0_1245:
	global_load_dwordx4 v[118:121], v[116:117], off offset:512 nt
	s_nop 0
	global_load_dwordx4 v[122:125], v[116:117], off offset:528 nt
	s_and_b64 vcc, exec, s[12:13]
	s_waitcnt vmcnt(1)
	v_pk_add_f32 v[102:103], v[102:103], v[120:121]
	v_pk_add_f32 v[100:101], v[100:101], v[118:119]
	s_waitcnt vmcnt(0)
	v_pk_add_f32 v[98:99], v[98:99], v[124:125]
	v_pk_add_f32 v[96:97], v[96:97], v[122:123]
	global_store_dwordx4 v[116:117], v[100:103], off offset:512 nt
	global_store_dwordx4 v[116:117], v[96:99], off offset:528 nt
	s_cbranch_vccnz .LBB0_1247
	v_lshlrev_b64 v[118:119], 1, v[114:115]
	v_or_b32_e32 v118, 0x100, v118
	v_cvt_pk_bf16_f32 v114, v100, v101
	v_cvt_pk_bf16_f32 v115, v102, v103
	v_cvt_pk_bf16_f32 v116, v96, v97
	v_cvt_pk_bf16_f32 v117, v98, v99
	v_lshl_add_u64 v[118:119], s[72:73], 0, v[118:119]
	global_store_dwordx4 v[118:119], v[114:117], off

; __device__ __forceinline__ unsigned cvt_pk_bf16(float lo, float hi) { f32x2_t v = {lo, hi}; bf16x2_t b = __builtin_convertvector(v, bf16x2_t); return __builtin_bit_cast(unsigned, b); }
;     __device__ __forceinline__ void operator()(const Acc& acc, const Unit& u, int wr, int wc, int fr, int fq) const {
;     ...
;                     const size_t off = (size_t)row * DM + col0 + bj * HALF;
;                     const f32x4 b0 = *(const f32x4*)(base + off), b1 = *(const f32x4*)(base + off + 4);
;                     const f32x4 x0 = b0 + acc[ai][bj][m][0] * alpha, x1 = b1 + acc[ai][bj][m][1] * alpha;
;                     __builtin_nontemporal_store(x0, (f32x4*)(out + off)); __builtin_nontemporal_store(x1, (f32x4*)(out + off + 4));
;                     sq += (x0[0] * x0[0] + x0[1] * x0[1]) + (x0[2] * x0[2] + x0[3] * x0[3]) + (x1[0] * x1[0] + x1[1] * x1[1]) + (x1[2] * x1[2] + x1[3] * x1[3]);
;                     if (xb) { u32x4 w; w.x = cvt_pk_bf16(x0[0], x0[1]); w.y = cvt_pk_bf16(x0[2], x0[3]); w.z = cvt_pk_bf16(x1[0], x1[1]); w.w = cvt_pk_bf16(x1[2], x1[3]); *(u32x4*)(xb + off) = w; }
.LBB0_1249:
	s_or_b64 exec, exec, s[6:7]
	v_or_b32_e32 v96, 32, v146
	s_waitcnt lgkmcnt(0)
	v_ashrrev_i32_e32 v97, 31, v96
	v_lshlrev_b64 v[98:99], 10, v[96:97]
	v_lshl_add_u64 v[98:99], v[98:99], 0, v[144:145]
	v_lshl_add_u64 v[100:101], v[98:99], 2, s[82:83]
	global_load_dwordx4 v[102:105], v[100:101], off nt
	global_load_dwordx4 v[106:109], v[100:101], off offset:16 nt
	s_and_b64 vcc, exec, s[12:13]
	s_waitcnt vmcnt(1)
	v_pk_add_f32 v[94:95], v[94:95], v[104:105]
	v_pk_add_f32 v[92:93], v[92:93], v[102:103]
	s_waitcnt vmcnt(0)
	v_pk_add_f32 v[90:91], v[90:91], v[108:109]
	v_pk_add_f32 v[88:89], v[88:89], v[106:107]
	global_store_dwordx4 v[100:101], v[92:95], off nt
	global_store_dwordx4 v[100:101], v[88:91], off offset:16 nt
	s_cbranch_vccnz .LBB0_1251
	v_cvt_pk_bf16_f32 v102, v92, v93
	v_cvt_pk_bf16_f32 v103, v94, v95
	v_cvt_pk_bf16_f32 v104, v88, v89
	v_cvt_pk_bf16_f32 v105, v90, v91
	v_lshl_add_u64 v[106:107], v[98:99], 1, s[72:73]
	global_store_dwordx4 v[106:107], v[102:105], off
.LBB0_1251:
	global_load_dwordx4 v[102:105], v[100:101], off offset:512 nt
	s_nop 0
	global_load_dwordx4 v[106:109], v[100:101], off offset:528 nt
	s_and_b64 vcc, exec, s[12:13]
	s_waitcnt vmcnt(1)
	v_pk_add_f32 v[86:87], v[86:87], v[104:105]
	v_pk_add_f32 v[84:85], v[84:85], v[102:103]
	s_waitcnt vmcnt(0)
	v_pk_add_f32 v[82:83], v[82:83], v[108:109]
	v_pk_add_f32 v[80:81], v[80:81], v[106:107]
	global_store_dwordx4 v[100:101], v[84:87], off offset:512 nt
	global_store_dwordx4 v[100:101], v[80:83], off offset:528 nt
	s_cbranch_vccnz .LBB0_1253
	v_lshlrev_b64 v[102:103], 1, v[98:99]
	v_or_b32_e32 v102, 0x100, v102
	v_cvt_pk_bf16_f32 v98, v84, v85
	v_cvt_pk_bf16_f32 v99, v86, v87
	v_cvt_pk_bf16_f32 v100, v80, v81
	v_cvt_pk_bf16_f32 v101, v82, v83
	v_lshl_add_u64 v[102:103], s[72:73], 0, v[102:103]
	global_store_dwordx4 v[102:103], v[98:101], off

; __device__ __forceinline__ unsigned cvt_pk_bf16(float lo, float hi) { f32x2_t v = {lo, hi}; bf16x2_t b = __builtin_convertvector(v, bf16x2_t); return __builtin_bit_cast(unsigned, b); }
;     __device__ __forceinline__ void operator()(const Acc& acc, const Unit& u, int wr, int wc, int fr, int fq) const {
;     ...
;                     const size_t off = (size_t)row * DM + col0 + bj * HALF;
;                     const f32x4 b0 = *(const f32x4*)(base + off), b1 = *(const f32x4*)(base + off + 4);
;                     const f32x4 x0 = b0 + acc[ai][bj][m][0] * alpha, x1 = b1 + acc[ai][bj][m][1] * alpha;
;                     __builtin_nontemporal_store(x0, (f32x4*)(out + off)); __builtin_nontemporal_store(x1, (f32x4*)(out + off + 4));
;                     sq += (x0[0] * x0[0] + x0[1] * x0[1]) + (x0[2] * x0[2] + x0[3] * x0[3]) + (x1[0] * x1[0] + x1[1] * x1[1]) + (x1[2] * x1[2] + x1[3] * x1[3]);
;                     if (xb) { u32x4 w; w.x = cvt_pk_bf16(x0[0], x0[1]); w.y = cvt_pk_bf16(x0[2], x0[3]); w.z = cvt_pk_bf16(x1[0], x1[1]); w.w = cvt_pk_bf16(x1[2], x1[3]); *(u32x4*)(xb + off) = w; }
.LBB0_1255:
	s_or_b64 exec, exec, s[6:7]
	v_or_b32_e32 v80, 48, v146
	s_waitcnt lgkmcnt(0)
	v_ashrrev_i32_e32 v81, 31, v80
	v_lshlrev_b64 v[82:83], 10, v[80:81]
	v_lshl_add_u64 v[82:83], v[82:83], 0, v[144:145]
	v_lshl_add_u64 v[84:85], v[82:83], 2, s[82:83]
	global_load_dwordx4 v[86:89], v[84:85], off nt
	global_load_dwordx4 v[90:93], v[84:85], off offset:16 nt
	s_and_b64 vcc, exec, s[12:13]
	s_waitcnt vmcnt(1)
	v_pk_add_f32 v[78:79], v[78:79], v[88:89]
	v_pk_add_f32 v[76:77], v[76:77], v[86:87]
	s_waitcnt vmcnt(0)
	v_pk_add_f32 v[74:75], v[74:75], v[92:93]
	v_pk_add_f32 v[72:73], v[72:73], v[90:91]
	global_store_dwordx4 v[84:85], v[76:79], off nt
	global_store_dwordx4 v[84:85], v[72:75], off offset:16 nt
	s_cbranch_vccnz .LBB0_1257
	v_cvt_pk_bf16_f32 v86, v76, v77
	v_cvt_pk_bf16_f32 v87, v78, v79
	v_cvt_pk_bf16_f32 v88, v72, v73
	v_cvt_pk_bf16_f32 v89, v74, v75
	v_lshl_add_u64 v[90:91], v[82:83], 1, s[72:73]
	global_store_dwordx4 v[90:91], v[86:89], off
.LBB0_1257:
	global_load_dwordx4 v[86:89], v[84:85], off offset:512 nt
	s_nop 0
	global_load_dwordx4 v[90:93], v[84:85], off offset:528 nt
	s_and_b64 vcc, exec, s[12:13]
	s_waitcnt vmcnt(1)
	v_pk_add_f32 v[70:71], v[70:71], v[88:89]
	v_pk_add_f32 v[68:69], v[68:69], v[86:87]
	s_waitcnt vmcnt(0)
	v_pk_add_f32 v[66:67], v[66:67], v[92:93]
	v_pk_add_f32 v[64:65], v[64:65], v[90:91]
	global_store_dwordx4 v[84:85], v[68:71], off offset:512 nt
	global_store_dwordx4 v[84:85], v[64:67], off offset:528 nt
	s_cbranch_vccnz .LBB0_1259
	v_lshlrev_b64 v[86:87], 1, v[82:83]
	v_or_b32_e32 v86, 0x100, v86
	v_cvt_pk_bf16_f32 v82, v68, v69
	v_cvt_pk_bf16_f32 v83, v70, v71
	v_cvt_pk_bf16_f32 v84, v64, v65
	v_cvt_pk_bf16_f32 v85, v66, v67
	v_lshl_add_u64 v[86:87], s[72:73], 0, v[86:87]
	global_store_dwordx4 v[86:87], v[82:85], off

; __device__ __forceinline__ unsigned cvt_pk_bf16(float lo, float hi) { f32x2_t v = {lo, hi}; bf16x2_t b = __builtin_convertvector(v, bf16x2_t); return __builtin_bit_cast(unsigned, b); }
;     __device__ __forceinline__ void operator()(const Acc& acc, const Unit& u, int wr, int wc, int fr, int fq) const {
;     ...
;                     const size_t off = (size_t)row * DM + col0 + bj * HALF;
;                     const f32x4 b0 = *(const f32x4*)(base + off), b1 = *(const f32x4*)(base + off + 4);
;                     const f32x4 x0 = b0 + acc[ai][bj][m][0] * alpha, x1 = b1 + acc[ai][bj][m][1] * alpha;
;                     __builtin_nontemporal_store(x0, (f32x4*)(out + off)); __builtin_nontemporal_store(x1, (f32x4*)(out + off + 4));
;                     sq += (x0[0] * x0[0] + x0[1] * x0[1]) + (x0[2] * x0[2] + x0[3] * x0[3]) + (x1[0] * x1[0] + x1[1] * x1[1]) + (x1[2] * x1[2] + x1[3] * x1[3]);
;                     if (xb) { u32x4 w; w.x = cvt_pk_bf16(x0[0], x0[1]); w.y = cvt_pk_bf16(x0[2], x0[3]); w.z = cvt_pk_bf16(x1[0], x1[1]); w.w = cvt_pk_bf16(x1[2], x1[3]); *(u32x4*)(xb + off) = w; }
.LBB0_1261:
	s_or_b64 exec, exec, s[6:7]
	v_add_u32_e32 v64, 0x80, v146
	s_waitcnt lgkmcnt(0)
	v_ashrrev_i32_e32 v65, 31, v64
	v_lshlrev_b64 v[66:67], 10, v[64:65]
	v_lshl_add_u64 v[66:67], v[66:67], 0, v[144:145]
	v_lshl_add_u64 v[68:69], v[66:67], 2, s[82:83]
	global_load_dwordx4 v[70:73], v[68:69], off nt
	global_load_dwordx4 v[74:77], v[68:69], off offset:16 nt
	s_and_b64 vcc, exec, s[12:13]
	s_waitcnt vmcnt(1)
	v_pk_add_f32 v[62:63], v[62:63], v[72:73]
	v_pk_add_f32 v[60:61], v[60:61], v[70:71]
	s_waitcnt vmcnt(0)
	v_pk_add_f32 v[58:59], v[58:59], v[76:77]
	v_pk_add_f32 v[56:57], v[56:57], v[74:75]
	global_store_dwordx4 v[68:69], v[60:63], off nt
	global_store_dwordx4 v[68:69], v[56:59], off offset:16 nt
	s_cbranch_vccnz .LBB0_1263
	v_cvt_pk_bf16_f32 v70, v60, v61
	v_cvt_pk_bf16_f32 v71, v62, v63
	v_cvt_pk_bf16_f32 v72, v56, v57
	v_cvt_pk_bf16_f32 v73, v58, v59
	v_lshl_add_u64 v[74:75], v[66:67], 1, s[72:73]
	global_store_dwordx4 v[74:75], v[70:73], off
.LBB0_1263:
	global_load_dwordx4 v[70:73], v[68:69], off offset:512 nt
	s_nop 0
	global_load_dwordx4 v[74:77], v[68:69], off offset:528 nt
	s_and_b64 vcc, exec, s[12:13]
	s_waitcnt vmcnt(1)
	v_pk_add_f32 v[54:55], v[54:55], v[72:73]
	v_pk_add_f32 v[52:53], v[52:53], v[70:71]
	s_waitcnt vmcnt(0)
	v_pk_add_f32 v[50:51], v[50:51], v[76:77]
	v_pk_add_f32 v[48:49], v[48:49], v[74:75]
	global_store_dwordx4 v[68:69], v[52:55], off offset:512 nt
	global_store_dwordx4 v[68:69], v[48:51], off offset:528 nt
	s_cbranch_vccnz .LBB0_1265
	v_lshlrev_b64 v[70:71], 1, v[66:67]
	v_or_b32_e32 v70, 0x100, v70
	v_cvt_pk_bf16_f32 v66, v52, v53
	v_cvt_pk_bf16_f32 v67, v54, v55
	v_cvt_pk_bf16_f32 v68, v48, v49
	v_cvt_pk_bf16_f32 v69, v50, v51
	v_lshl_add_u64 v[70:71], s[72:73], 0, v[70:71]
	global_store_dwordx4 v[70:71], v[66:69], off

; __device__ __forceinline__ unsigned cvt_pk_bf16(float lo, float hi) { f32x2_t v = {lo, hi}; bf16x2_t b = __builtin_convertvector(v, bf16x2_t); return __builtin_bit_cast(unsigned, b); }
;     __device__ __forceinline__ void operator()(const Acc& acc, const Unit& u, int wr, int wc, int fr, int fq) const {
;     ...
;                     const size_t off = (size_t)row * DM + col0 + bj * HALF;
;                     const f32x4 b0 = *(const f32x4*)(base + off), b1 = *(const f32x4*)(base + off + 4);
;                     const f32x4 x0 = b0 + acc[ai][bj][m][0] * alpha, x1 = b1 + acc[ai][bj][m][1] * alpha;
;                     __builtin_nontemporal_store(x0, (f32x4*)(out + off)); __builtin_nontemporal_store(x1, (f32x4*)(out + off + 4));
;                     sq += (x0[0] * x0[0] + x0[1] * x0[1]) + (x0[2] * x0[2] + x0[3] * x0[3]) + (x1[0] * x1[0] + x1[1] * x1[1]) + (x1[2] * x1[2] + x1[3] * x1[3]);
;                     if (xb) { u32x4 w; w.x = cvt_pk_bf16(x0[0], x0[1]); w.y = cvt_pk_bf16(x0[2], x0[3]); w.z = cvt_pk_bf16(x1[0], x1[1]); w.w = cvt_pk_bf16(x1[2], x1[3]); *(u32x4*)(xb + off) = w; }
.LBB0_1267:
	s_or_b64 exec, exec, s[6:7]
	v_add_u32_e32 v48, 0x90, v146
	s_waitcnt lgkmcnt(0)
	v_ashrrev_i32_e32 v49, 31, v48
	v_lshlrev_b64 v[50:51], 10, v[48:49]
	v_lshl_add_u64 v[50:51], v[50:51], 0, v[144:145]
	v_lshl_add_u64 v[52:53], v[50:51], 2, s[82:83]
	global_load_dwordx4 v[54:57], v[52:53], off nt
	global_load_dwordx4 v[58:61], v[52:53], off offset:16 nt
	s_and_b64 vcc, exec, s[12:13]
	s_waitcnt vmcnt(1)
	v_pk_add_f32 v[46:47], v[46:47], v[56:57]
	v_pk_add_f32 v[44:45], v[44:45], v[54:55]
	s_waitcnt vmcnt(0)
	v_pk_add_f32 v[42:43], v[42:43], v[60:61]
	v_pk_add_f32 v[40:41], v[40:41], v[58:59]
	global_store_dwordx4 v[52:53], v[44:47], off nt
	global_store_dwordx4 v[52:53], v[40:43], off offset:16 nt
	s_cbranch_vccnz .LBB0_1269
	v_cvt_pk_bf16_f32 v54, v44, v45
	v_cvt_pk_bf16_f32 v55, v46, v47
	v_cvt_pk_bf16_f32 v56, v40, v41
	v_cvt_pk_bf16_f32 v57, v42, v43
	v_lshl_add_u64 v[58:59], v[50:51], 1, s[72:73]
	global_store_dwordx4 v[58:59], v[54:57], off
.LBB0_1269:
	global_load_dwordx4 v[54:57], v[52:53], off offset:512 nt
	s_nop 0
	global_load_dwordx4 v[58:61], v[52:53], off offset:528 nt
	s_and_b64 vcc, exec, s[12:13]
	s_waitcnt vmcnt(1)
	v_pk_add_f32 v[38:39], v[38:39], v[56:57]
	v_pk_add_f32 v[36:37], v[36:37], v[54:55]
	s_waitcnt vmcnt(0)
	v_pk_add_f32 v[34:35], v[34:35], v[60:61]
	v_pk_add_f32 v[32:33], v[32:33], v[58:59]
	global_store_dwordx4 v[52:53], v[36:39], off offset:512 nt
	global_store_dwordx4 v[52:53], v[32:35], off offset:528 nt
	s_cbranch_vccnz .LBB0_1271
	v_lshlrev_b64 v[54:55], 1, v[50:51]
	v_or_b32_e32 v54, 0x100, v54
	v_cvt_pk_bf16_f32 v50, v36, v37
	v_cvt_pk_bf16_f32 v51, v38, v39
	v_cvt_pk_bf16_f32 v52, v32, v33
	v_cvt_pk_bf16_f32 v53, v34, v35
	v_lshl_add_u64 v[54:55], s[72:73], 0, v[54:55]
	global_store_dwordx4 v[54:55], v[50:53], off

; __device__ __forceinline__ unsigned cvt_pk_bf16(float lo, float hi) { f32x2_t v = {lo, hi}; bf16x2_t b = __builtin_convertvector(v, bf16x2_t); return __builtin_bit_cast(unsigned, b); }
;     __device__ __forceinline__ void operator()(const Acc& acc, const Unit& u, int wr, int wc, int fr, int fq) const {
;     ...
;                 const int row = row0 + ai * HALF + m * 16; float sq = 0.f;
; #pragma unroll
;                 for (int bj = 0; bj < 2; ++bj) {
;                     const size_t off = (size_t)row * DM + col0 + bj * HALF;
;                     const f32x4 b0 = *(const f32x4*)(base + off), b1 = *(const f32x4*)(base + off + 4);
;                     const f32x4 x0 = b0 + acc[ai][bj][m][0] * alpha, x1 = b1 + acc[ai][bj][m][1] * alpha;
;                     __builtin_nontemporal_store(x0, (f32x4*)(out + off)); __builtin_nontemporal_store(x1, (f32x4*)(out + off + 4));
;                     sq += (x0[0] * x0[0] + x0[1] * x0[1]) + (x0[2] * x0[2] + x0[3] * x0[3]) + (x1[0] * x1[0] + x1[1] * x1[1]) + (x1[2] * x1[2] + x1[3] * x1[3]);
;                     if (xb) { u32x4 w; w.x = cvt_pk_bf16(x0[0], x0[1]); w.y = cvt_pk_bf16(x0[2], x0[3]); w.z = cvt_pk_bf16(x1[0], x1[1]); w.w = cvt_pk_bf16(x1[2], x1[3]); *(u32x4*)(xb + off) = w; }
.LBB0_1273:
	s_or_b64 exec, exec, s[6:7]
	v_add_u32_e32 v32, 0xa0, v146
	s_waitcnt lgkmcnt(0)
	v_ashrrev_i32_e32 v33, 31, v32
	v_lshlrev_b64 v[34:35], 10, v[32:33]
	v_lshl_add_u64 v[34:35], v[34:35], 0, v[144:145]
	v_lshl_add_u64 v[36:37], v[34:35], 2, s[82:83]
	global_load_dwordx4 v[38:41], v[36:37], off nt
	global_load_dwordx4 v[42:45], v[36:37], off offset:16 nt
	s_and_b64 vcc, exec, s[12:13]
	s_waitcnt vmcnt(1)
	v_pk_add_f32 v[30:31], v[30:31], v[40:41]
	v_pk_add_f32 v[28:29], v[28:29], v[38:39]
	s_waitcnt vmcnt(0)
	v_pk_add_f32 v[26:27], v[26:27], v[44:45]
	v_pk_add_f32 v[24:25], v[24:25], v[42:43]
	global_store_dwordx4 v[36:37], v[28:31], off nt
	global_store_dwordx4 v[36:37], v[24:27], off offset:16 nt
	s_cbranch_vccnz .LBB0_1275
	v_cvt_pk_bf16_f32 v38, v28, v29
	v_cvt_pk_bf16_f32 v39, v30, v31
	v_cvt_pk_bf16_f32 v40, v24, v25
	v_cvt_pk_bf16_f32 v41, v26, v27
	v_lshl_add_u64 v[42:43], v[34:35], 1, s[72:73]
	global_store_dwordx4 v[42:43], v[38:41], off
.LBB0_1275:
	global_load_dwordx4 v[38:41], v[36:37], off offset:512 nt
	s_nop 0
	global_load_dwordx4 v[42:45], v[36:37], off offset:528 nt
	s_and_b64 vcc, exec, s[12:13]
	s_waitcnt vmcnt(1)
	v_pk_add_f32 v[22:23], v[22:23], v[40:41]
	v_pk_add_f32 v[20:21], v[20:21], v[38:39]
	s_waitcnt vmcnt(0)
	v_pk_add_f32 v[18:19], v[18:19], v[44:45]
	v_pk_add_f32 v[16:17], v[16:17], v[42:43]
	global_store_dwordx4 v[36:37], v[20:23], off offset:512 nt
	global_store_dwordx4 v[36:37], v[16:19], off offset:528 nt
	s_cbranch_vccnz .LBB0_1277
	v_lshlrev_b64 v[38:39], 1, v[34:35]
	v_or_b32_e32 v38, 0x100, v38
	v_cvt_pk_bf16_f32 v34, v20, v21
	v_cvt_pk_bf16_f32 v35, v22, v23
	v_cvt_pk_bf16_f32 v36, v16, v17
	v_cvt_pk_bf16_f32 v37, v18, v19
	v_lshl_add_u64 v[38:39], s[72:73], 0, v[38:39]
	global_store_dwordx4 v[38:39], v[34:37], off

; __device__ __forceinline__ unsigned cvt_pk_bf16(float lo, float hi) { f32x2_t v = {lo, hi}; bf16x2_t b = __builtin_convertvector(v, bf16x2_t); return __builtin_bit_cast(unsigned, b); }
;     __device__ __forceinline__ void operator()(const Acc& acc, const Unit& u, int wr, int wc, int fr, int fq) const {
;     ...
;                 const int row = row0 + ai * HALF + m * 16; float sq = 0.f;
; #pragma unroll
;                 for (int bj = 0; bj < 2; ++bj) {
;                     const size_t off = (size_t)row * DM + col0 + bj * HALF;
;                     const f32x4 b0 = *(const f32x4*)(base + off), b1 = *(const f32x4*)(base + off + 4);
;                     const f32x4 x0 = b0 + acc[ai][bj][m][0] * alpha, x1 = b1 + acc[ai][bj][m][1] * alpha;
;                     __builtin_nontemporal_store(x0, (f32x4*)(out + off)); __builtin_nontemporal_store(x1, (f32x4*)(out + off + 4));
;                     sq += (x0[0] * x0[0] + x0[1] * x0[1]) + (x0[2] * x0[2] + x0[3] * x0[3]) + (x1[0] * x1[0] + x1[1] * x1[1]) + (x1[2] * x1[2] + x1[3] * x1[3]);
;                     if (xb) { u32x4 w; w.x = cvt_pk_bf16(x0[0], x0[1]); w.y = cvt_pk_bf16(x0[2], x0[3]); w.z = cvt_pk_bf16(x1[0], x1[1]); w.w = cvt_pk_bf16(x1[2], x1[3]); *(u32x4*)(xb + off) = w; }
.LBB0_1279:
	s_or_b64 exec, exec, s[6:7]
	v_add_u32_e32 v16, 0xb0, v146
	s_waitcnt lgkmcnt(0)
	v_ashrrev_i32_e32 v17, 31, v16
	v_lshlrev_b64 v[18:19], 10, v[16:17]
	v_lshl_add_u64 v[18:19], v[18:19], 0, v[144:145]
	v_lshl_add_u64 v[20:21], v[18:19], 2, s[82:83]
	global_load_dwordx4 v[22:25], v[20:21], off nt
	global_load_dwordx4 v[26:29], v[20:21], off offset:16 nt
	s_and_b64 vcc, exec, s[12:13]
	s_waitcnt vmcnt(1)
	v_pk_add_f32 v[14:15], v[14:15], v[24:25]
	v_pk_add_f32 v[12:13], v[12:13], v[22:23]
	s_waitcnt vmcnt(0)
	v_pk_add_f32 v[10:11], v[10:11], v[28:29]
	v_pk_add_f32 v[8:9], v[8:9], v[26:27]
	global_store_dwordx4 v[20:21], v[12:15], off nt
	global_store_dwordx4 v[20:21], v[8:11], off offset:16 nt
	s_cbranch_vccnz .LBB0_1281
	v_cvt_pk_bf16_f32 v22, v12, v13
	v_cvt_pk_bf16_f32 v23, v14, v15
	v_cvt_pk_bf16_f32 v24, v8, v9
	v_cvt_pk_bf16_f32 v25, v10, v11
	v_lshl_add_u64 v[26:27], v[18:19], 1, s[72:73]
	global_store_dwordx4 v[26:27], v[22:25], off
.LBB0_1281:
	global_load_dwordx4 v[22:25], v[20:21], off offset:512 nt
	s_nop 0
	global_load_dwordx4 v[26:29], v[20:21], off offset:528 nt
	s_and_b64 vcc, exec, s[12:13]
	s_waitcnt vmcnt(1)
	v_pk_add_f32 v[6:7], v[6:7], v[24:25]
	v_pk_add_f32 v[4:5], v[4:5], v[22:23]
	s_waitcnt vmcnt(0)
	v_pk_add_f32 v[2:3], v[2:3], v[28:29]
	v_pk_add_f32 v[0:1], v[0:1], v[26:27]
	global_store_dwordx4 v[20:21], v[4:7], off offset:512 nt
	global_store_dwordx4 v[20:21], v[0:3], off offset:528 nt
	s_cbranch_vccnz .LBB0_1283
	v_lshlrev_b64 v[22:23], 1, v[18:19]
	v_or_b32_e32 v22, 0x100, v22
	v_cvt_pk_bf16_f32 v18, v4, v5
	v_cvt_pk_bf16_f32 v19, v6, v7
	v_cvt_pk_bf16_f32 v20, v0, v1
	v_cvt_pk_bf16_f32 v21, v2, v3
	v_lshl_add_u64 v[22:23], s[72:73], 0, v[22:23]
	global_store_dwordx4 v[22:23], v[18:21], off

;     __device__ __forceinline__ void operator()(Acc& acc, const Unit& u, int wr, int wc, int fr, int fq) const {
;     ...
;                 const int rt = rt0 + ai * HALF + m * 16; float sq = 0.f;
; #pragma unroll
;                 for (int bj = 0; bj < 2; ++bj) {
;                     const size_t off = (size_t)(u.pm * BM + rt) * DM + col0 + bj * HALF;
;                     const f32x4 b0 = *(const f32x4*)(base + off), b1 = *(const f32x4*)(base + off + 4);
;                     const f32x4 x0 = b0 + acc[ai][bj][m][0] * alpha, x1 = b1 + acc[ai][bj][m][1] * alpha;
;                     acc[ai][bj][m][0] = x0; acc[ai][bj][m][1] = x1;
;                     sq += (x0[0] * x0[0] + x0[1] * x0[1]) + (x0[2] * x0[2] + x0[3] * x0[3]) + (x1[0] * x1[0] + x1[1] * x1[1]) + (x1[2] * x1[2] + x1[3] * x1[3]);
;                 }
;                 sq += __shfl_xor(sq, 16); sq += __shfl_xor(sq, 32);
;                 if (fq == 0) P[rt * 4 + wc] = sq;
.LBB0_1436:
	s_lshl_b32 s25, s49, 8
	v_add_u32_e32 v144, s25, v183
	v_ashrrev_i32_e32 v145, 31, v144
	v_lshl_or_b32 v154, s24, 8, v185
	v_lshlrev_b64 v[144:145], 12, v[144:145]
	v_ashrrev_i32_e32 v155, 31, v154
	v_lshl_add_u64 v[144:145], s[82:83], 0, v[144:145]
	v_lshl_add_u64 v[144:145], v[154:155], 2, v[144:145]
	global_load_dwordx4 v[146:149], v[144:145], off nt
	global_load_dwordx4 v[150:153], v[144:145], off offset:16 nt
	global_load_dwordx4 v[156:159], v[144:145], off offset:512 nt
	global_load_dwordx4 v[160:163], v[144:145], off offset:528 nt
	s_waitcnt vmcnt(0)
	v_pk_fma_f32 v[126:127], v[126:127], 0.5, v[148:149] op_sel_hi:[1,0,1]
	v_pk_fma_f32 v[124:125], v[124:125], 0.5, v[146:147] op_sel_hi:[1,0,1]
	v_pk_fma_f32 v[118:119], v[118:119], 0.5, v[158:159] op_sel_hi:[1,0,1]
	v_pk_fma_f32 v[116:117], v[116:117], 0.5, v[156:157] op_sel_hi:[1,0,1]
	v_pk_fma_f32 v[120:121], v[120:121], 0.5, v[150:151] op_sel_hi:[1,0,1]
	v_pk_fma_f32 v[146:147], v[112:113], 0.5, v[160:161] op_sel_hi:[1,0,1]
	v_mul_f32_e32 v112, v125, v125
	v_mul_f32_e32 v113, v127, v127
	v_mul_f32_e32 v150, v117, v117
	v_mul_f32_e32 v151, v119, v119
	v_pk_fma_f32 v[122:123], v[122:123], 0.5, v[152:153] op_sel_hi:[1,0,1]
	v_pk_fma_f32 v[114:115], v[114:115], 0.5, v[162:163] op_sel_hi:[1,0,1]
	v_mul_f32_e32 v148, v121, v121
	v_mul_f32_e32 v152, v147, v147
	v_fmac_f32_e32 v112, v124, v124
	v_fmac_f32_e32 v113, v126, v126
	v_fmac_f32_e32 v150, v116, v116
	v_fmac_f32_e32 v151, v118, v118
	v_mul_f32_e32 v149, v123, v123
	v_mul_f32_e32 v153, v115, v115
	v_fmac_f32_e32 v148, v120, v120
	v_fmac_f32_e32 v152, v146, v146
	v_add_f32_e32 v112, v112, v113
	v_add_f32_e32 v113, v150, v151
	v_fmac_f32_e32 v149, v122, v122
	v_fmac_f32_e32 v153, v114, v114
	v_add_f32_e32 v112, v148, v112
	v_add_f32_e32 v113, v152, v113
	v_add_f32_e32 v112, v149, v112
	v_add_f32_e32 v113, v153, v113
	v_add_f32_e32 v112, v112, v113
	ds_bpermute_b32 v113, v181, v112
	s_waitcnt lgkmcnt(0)
	v_add_f32_e32 v112, v112, v113
	ds_bpermute_b32 v113, v182, v112
	s_and_saveexec_b64 s[26:27], s[2:3]
	s_cbranch_execz .LBB0_1438
	s_waitcnt lgkmcnt(0)
	v_add_f32_e32 v112, v112, v113
	ds_write_b32 v205, v112
.LBB0_1438:
	s_or_b64 exec, exec, s[26:27]
	v_add_u32_e32 v112, s25, v186
	s_waitcnt lgkmcnt(0)
	v_ashrrev_i32_e32 v113, 31, v112
	v_lshlrev_b64 v[112:113], 12, v[112:113]
	v_lshl_add_u64 v[112:113], s[82:83], 0, v[112:113]
	v_lshl_add_u64 v[112:113], v[154:155], 2, v[112:113]
	global_load_dwordx4 v[148:151], v[112:113], off nt
	global_load_dwordx4 v[156:159], v[112:113], off offset:16 nt
	global_load_dwordx4 v[160:163], v[112:113], off offset:512 nt
	global_load_dwordx4 v[164:167], v[112:113], off offset:528 nt
	s_waitcnt vmcnt(3)
	v_pk_fma_f32 v[110:111], v[110:111], 0.5, v[150:151] op_sel_hi:[1,0,1]
	v_pk_fma_f32 v[108:109], v[108:109], 0.5, v[148:149] op_sel_hi:[1,0,1]
	s_waitcnt vmcnt(1)
	v_pk_fma_f32 v[102:103], v[102:103], 0.5, v[162:163] op_sel_hi:[1,0,1]
	v_pk_fma_f32 v[100:101], v[100:101], 0.5, v[160:161] op_sel_hi:[1,0,1]
	v_pk_fma_f32 v[104:105], v[104:105], 0.5, v[156:157] op_sel_hi:[1,0,1]
	s_waitcnt vmcnt(0)
	v_pk_fma_f32 v[96:97], v[96:97], 0.5, v[164:165] op_sel_hi:[1,0,1]
	v_mul_f32_e32 v148, v109, v109
	v_mul_f32_e32 v149, v111, v111
	v_mul_f32_e32 v152, v101, v101
	v_mul_f32_e32 v153, v103, v103
	v_pk_fma_f32 v[106:107], v[106:107], 0.5, v[158:159] op_sel_hi:[1,0,1]
	v_pk_fma_f32 v[98:99], v[98:99], 0.5, v[166:167] op_sel_hi:[1,0,1]
	v_mul_f32_e32 v150, v105, v105
	v_mul_f32_e32 v156, v97, v97
	v_fmac_f32_e32 v148, v108, v108
	v_fmac_f32_e32 v149, v110, v110
	v_fmac_f32_e32 v152, v100, v100
	v_fmac_f32_e32 v153, v102, v102
	v_mul_f32_e32 v151, v107, v107
	v_mul_f32_e32 v157, v99, v99
	v_fmac_f32_e32 v150, v104, v104
	v_fmac_f32_e32 v156, v96, v96
	v_add_f32_e32 v148, v148, v149
	v_add_f32_e32 v149, v152, v153
	v_fmac_f32_e32 v151, v106, v106
	v_fmac_f32_e32 v157, v98, v98
	v_add_f32_e32 v148, v150, v148
	v_add_f32_e32 v149, v156, v149
	v_add_f32_e32 v148, v151, v148
	v_add_f32_e32 v149, v157, v149
	v_add_f32_e32 v148, v148, v149
	ds_bpermute_b32 v149, v181, v148
	s_waitcnt lgkmcnt(0)
	v_add_f32_e32 v148, v148, v149
	ds_bpermute_b32 v149, v182, v148
	s_mov_b64 s[26:27], exec
	s_and_b64 s[34:35], s[26:27], s[2:3]
	v_mov_b32_e32 v246, v180
	s_mov_b64 exec, s[34:35]
	s_cbranch_execz .LBB0_1440
	s_waitcnt lgkmcnt(0)
	v_add_f32_e32 v148, v148, v149
	ds_write_b32 v206, v148
.LBB0_1440:
	s_or_b64 exec, exec, s[26:27]
	v_add_u32_e32 v148, s25, v187
	s_waitcnt lgkmcnt(0)
	v_ashrrev_i32_e32 v149, 31, v148
	v_lshlrev_b64 v[148:149], 12, v[148:149]
	v_lshl_add_u64 v[148:149], s[82:83], 0, v[148:149]
	v_lshl_add_u64 v[148:149], v[154:155], 2, v[148:149]
	global_load_dwordx4 v[150:153], v[148:149], off nt
	global_load_dwordx4 v[156:159], v[148:149], off offset:16 nt
	global_load_dwordx4 v[160:163], v[148:149], off offset:512 nt
	global_load_dwordx4 v[164:167], v[148:149], off offset:528 nt
	s_waitcnt vmcnt(3)
	v_pk_fma_f32 v[94:95], v[94:95], 0.5, v[152:153] op_sel_hi:[1,0,1]
	v_pk_fma_f32 v[92:93], v[92:93], 0.5, v[150:151] op_sel_hi:[1,0,1]
	s_waitcnt vmcnt(1)
	v_pk_fma_f32 v[86:87], v[86:87], 0.5, v[162:163] op_sel_hi:[1,0,1]
	v_pk_fma_f32 v[84:85], v[84:85], 0.5, v[160:161] op_sel_hi:[1,0,1]
	v_pk_fma_f32 v[88:89], v[88:89], 0.5, v[156:157] op_sel_hi:[1,0,1]
	s_waitcnt vmcnt(0)
	v_pk_fma_f32 v[150:151], v[80:81], 0.5, v[164:165] op_sel_hi:[1,0,1]
	v_mul_f32_e32 v80, v93, v93
	v_mul_f32_e32 v81, v95, v95
	v_mul_f32_e32 v156, v85, v85
	v_mul_f32_e32 v157, v87, v87
	v_pk_fma_f32 v[90:91], v[90:91], 0.5, v[158:159] op_sel_hi:[1,0,1]
	v_pk_fma_f32 v[82:83], v[82:83], 0.5, v[166:167] op_sel_hi:[1,0,1]
	v_mul_f32_e32 v152, v89, v89
	v_mul_f32_e32 v158, v151, v151
	v_fmac_f32_e32 v80, v92, v92
	v_fmac_f32_e32 v81, v94, v94
	v_fmac_f32_e32 v156, v84, v84
	v_fmac_f32_e32 v157, v86, v86
	v_mul_f32_e32 v153, v91, v91
	v_mul_f32_e32 v159, v83, v83
	v_fmac_f32_e32 v152, v88, v88
	v_fmac_f32_e32 v158, v150, v150
	v_add_f32_e32 v80, v80, v81
	v_add_f32_e32 v81, v156, v157
	v_fmac_f32_e32 v153, v90, v90
	v_fmac_f32_e32 v159, v82, v82
	v_add_f32_e32 v80, v152, v80
	v_add_f32_e32 v81, v158, v81
	v_add_f32_e32 v80, v153, v80
	v_add_f32_e32 v81, v159, v81
	v_add_f32_e32 v80, v80, v81
	ds_bpermute_b32 v81, v181, v80
	s_waitcnt lgkmcnt(0)
	v_add_f32_e32 v80, v80, v81
	ds_bpermute_b32 v81, v182, v80
	s_and_saveexec_b64 s[26:27], s[2:3]
	s_cbranch_execz .LBB0_1442
	s_waitcnt lgkmcnt(0)
	v_add_f32_e32 v80, v80, v81
	ds_write_b32 v207, v80
;     __device__ __forceinline__ void operator()(Acc& acc, const Unit& u, int wr, int wc, int fr, int fq) const {
;     ...
;                 const int rt = rt0 + ai * HALF + m * 16; float sq = 0.f;
; #pragma unroll
;                 for (int bj = 0; bj < 2; ++bj) {
;                     const size_t off = (size_t)(u.pm * BM + rt) * DM + col0 + bj * HALF;
;                     const f32x4 b0 = *(const f32x4*)(base + off), b1 = *(const f32x4*)(base + off + 4);
;                     const f32x4 x0 = b0 + acc[ai][bj][m][0] * alpha, x1 = b1 + acc[ai][bj][m][1] * alpha;
;                     acc[ai][bj][m][0] = x0; acc[ai][bj][m][1] = x1;
;                     sq += (x0[0] * x0[0] + x0[1] * x0[1]) + (x0[2] * x0[2] + x0[3] * x0[3]) + (x1[0] * x1[0] + x1[1] * x1[1]) + (x1[2] * x1[2] + x1[3] * x1[3]);
;                 }
;                 sq += __shfl_xor(sq, 16); sq += __shfl_xor(sq, 32);
;                 if (fq == 0) P[rt * 4 + wc] = sq;
.LBB0_1442:
	s_or_b64 exec, exec, s[26:27]
	v_add_u32_e32 v80, s25, v188
	s_waitcnt lgkmcnt(0)
	v_ashrrev_i32_e32 v81, 31, v80
	v_lshlrev_b64 v[80:81], 12, v[80:81]
	v_lshl_add_u64 v[80:81], s[82:83], 0, v[80:81]
	v_lshl_add_u64 v[80:81], v[154:155], 2, v[80:81]
	global_load_dwordx4 v[156:159], v[80:81], off nt
	global_load_dwordx4 v[160:163], v[80:81], off offset:16 nt
	global_load_dwordx4 v[164:167], v[80:81], off offset:512 nt
	global_load_dwordx4 v[168:171], v[80:81], off offset:528 nt
	s_waitcnt vmcnt(3)
	v_pk_fma_f32 v[78:79], v[78:79], 0.5, v[158:159] op_sel_hi:[1,0,1]
	v_pk_fma_f32 v[152:153], v[76:77], 0.5, v[156:157] op_sel_hi:[1,0,1]
	s_waitcnt vmcnt(1)
	v_pk_fma_f32 v[70:71], v[70:71], 0.5, v[166:167] op_sel_hi:[1,0,1]
	v_pk_fma_f32 v[68:69], v[68:69], 0.5, v[164:165] op_sel_hi:[1,0,1]
	v_pk_fma_f32 v[76:77], v[72:73], 0.5, v[160:161] op_sel_hi:[1,0,1]
	s_waitcnt vmcnt(0)
	v_pk_fma_f32 v[64:65], v[64:65], 0.5, v[168:169] op_sel_hi:[1,0,1]
	v_mul_f32_e32 v72, v153, v153
	v_mul_f32_e32 v73, v79, v79
	v_mul_f32_e32 v158, v69, v69
	v_mul_f32_e32 v159, v71, v71
	v_pk_fma_f32 v[74:75], v[74:75], 0.5, v[162:163] op_sel_hi:[1,0,1]
	v_pk_fma_f32 v[66:67], v[66:67], 0.5, v[170:171] op_sel_hi:[1,0,1]
	v_mul_f32_e32 v156, v77, v77
	v_mul_f32_e32 v160, v65, v65
	v_fmac_f32_e32 v72, v152, v152
	v_fmac_f32_e32 v73, v78, v78
	v_fmac_f32_e32 v158, v68, v68
	v_fmac_f32_e32 v159, v70, v70
	v_mul_f32_e32 v157, v75, v75
	v_mul_f32_e32 v161, v67, v67
	v_fmac_f32_e32 v156, v76, v76
	v_fmac_f32_e32 v160, v64, v64
	v_add_f32_e32 v72, v72, v73
	v_add_f32_e32 v73, v158, v159
	v_fmac_f32_e32 v157, v74, v74
	v_fmac_f32_e32 v161, v66, v66
	v_add_f32_e32 v72, v156, v72
	v_add_f32_e32 v73, v160, v73
	v_add_f32_e32 v72, v157, v72
	v_add_f32_e32 v73, v161, v73
	v_add_f32_e32 v72, v72, v73
	ds_bpermute_b32 v73, v181, v72
	s_waitcnt lgkmcnt(0)
	v_add_f32_e32 v72, v72, v73
	ds_bpermute_b32 v73, v182, v72
	s_and_saveexec_b64 s[26:27], s[2:3]
	s_cbranch_execz .LBB0_1444
	s_waitcnt lgkmcnt(0)
	v_add_f32_e32 v72, v72, v73
	ds_write_b32 v208, v72
.LBB0_1444:
	s_or_b64 exec, exec, s[26:27]
	v_add_u32_e32 v72, s25, v189
	s_waitcnt lgkmcnt(0)
	v_ashrrev_i32_e32 v73, 31, v72
	v_lshlrev_b64 v[72:73], 12, v[72:73]
	v_lshl_add_u64 v[72:73], s[82:83], 0, v[72:73]
	v_lshl_add_u64 v[72:73], v[154:155], 2, v[72:73]
	global_load_dwordx4 v[156:159], v[72:73], off nt
	global_load_dwordx4 v[160:163], v[72:73], off offset:16 nt
	global_load_dwordx4 v[164:167], v[72:73], off offset:512 nt
	global_load_dwordx4 v[168:171], v[72:73], off offset:528 nt
	s_waitcnt vmcnt(3)
	v_pk_fma_f32 v[62:63], v[62:63], 0.5, v[158:159] op_sel_hi:[1,0,1]
	v_pk_fma_f32 v[60:61], v[60:61], 0.5, v[156:157] op_sel_hi:[1,0,1]
	s_waitcnt vmcnt(1)
	v_pk_fma_f32 v[54:55], v[54:55], 0.5, v[166:167] op_sel_hi:[1,0,1]
	v_pk_fma_f32 v[52:53], v[52:53], 0.5, v[164:165] op_sel_hi:[1,0,1]
	v_pk_fma_f32 v[56:57], v[56:57], 0.5, v[160:161] op_sel_hi:[1,0,1]
	s_waitcnt vmcnt(0)
	v_pk_fma_f32 v[48:49], v[48:49], 0.5, v[168:169] op_sel_hi:[1,0,1]
	v_mul_f32_e32 v156, v61, v61
	v_mul_f32_e32 v157, v63, v63
	v_mul_f32_e32 v160, v53, v53
	v_mul_f32_e32 v161, v55, v55
	v_pk_fma_f32 v[58:59], v[58:59], 0.5, v[162:163] op_sel_hi:[1,0,1]
	v_pk_fma_f32 v[50:51], v[50:51], 0.5, v[170:171] op_sel_hi:[1,0,1]
	v_mul_f32_e32 v158, v57, v57
	v_mul_f32_e32 v162, v49, v49
	v_fmac_f32_e32 v156, v60, v60
	v_fmac_f32_e32 v157, v62, v62
	v_fmac_f32_e32 v160, v52, v52
	v_fmac_f32_e32 v161, v54, v54
	v_mul_f32_e32 v159, v59, v59
	v_mul_f32_e32 v163, v51, v51
	v_fmac_f32_e32 v158, v56, v56
	v_fmac_f32_e32 v162, v48, v48
	v_add_f32_e32 v156, v156, v157
	v_add_f32_e32 v157, v160, v161
	v_fmac_f32_e32 v159, v58, v58
	v_fmac_f32_e32 v163, v50, v50
	v_add_f32_e32 v156, v158, v156
	v_add_f32_e32 v157, v162, v157
	v_add_f32_e32 v156, v159, v156
	v_add_f32_e32 v157, v163, v157
	v_add_f32_e32 v156, v156, v157
	ds_bpermute_b32 v157, v181, v156
	s_waitcnt lgkmcnt(0)
	v_add_f32_e32 v156, v156, v157
	ds_bpermute_b32 v157, v182, v156
	s_and_saveexec_b64 s[26:27], s[2:3]
	s_cbranch_execz .LBB0_1446
	s_waitcnt lgkmcnt(0)
	v_add_f32_e32 v156, v156, v157
	ds_write_b32 v209, v156
.LBB0_1446:
	s_or_b64 exec, exec, s[26:27]
	v_add_u32_e32 v156, s25, v190
	s_waitcnt lgkmcnt(0)
	v_ashrrev_i32_e32 v157, 31, v156
	v_lshlrev_b64 v[156:157], 12, v[156:157]
	v_lshl_add_u64 v[156:157], s[82:83], 0, v[156:157]
	v_lshl_add_u64 v[156:157], v[154:155], 2, v[156:157]
	global_load_dwordx4 v[158:161], v[156:157], off nt
	global_load_dwordx4 v[162:165], v[156:157], off offset:16 nt
	global_load_dwordx4 v[166:169], v[156:157], off offset:512 nt
	global_load_dwordx4 v[170:173], v[156:157], off offset:528 nt
	s_waitcnt vmcnt(3)
	v_pk_fma_f32 v[46:47], v[46:47], 0.5, v[160:161] op_sel_hi:[1,0,1]
	v_pk_fma_f32 v[44:45], v[44:45], 0.5, v[158:159] op_sel_hi:[1,0,1]
	s_waitcnt vmcnt(1)
	v_pk_fma_f32 v[38:39], v[38:39], 0.5, v[168:169] op_sel_hi:[1,0,1]
	v_pk_fma_f32 v[36:37], v[36:37], 0.5, v[166:167] op_sel_hi:[1,0,1]
	v_pk_fma_f32 v[40:41], v[40:41], 0.5, v[162:163] op_sel_hi:[1,0,1]
	s_waitcnt vmcnt(0)
	v_pk_fma_f32 v[32:33], v[32:33], 0.5, v[170:171] op_sel_hi:[1,0,1]
	v_mul_f32_e32 v158, v45, v45
	v_mul_f32_e32 v159, v47, v47
	v_mul_f32_e32 v162, v37, v37
	v_mul_f32_e32 v163, v39, v39
	v_pk_fma_f32 v[42:43], v[42:43], 0.5, v[164:165] op_sel_hi:[1,0,1]
	v_pk_fma_f32 v[34:35], v[34:35], 0.5, v[172:173] op_sel_hi:[1,0,1]
	v_mul_f32_e32 v160, v41, v41
	v_mul_f32_e32 v164, v33, v33
	v_fmac_f32_e32 v158, v44, v44
	v_fmac_f32_e32 v159, v46, v46
	v_fmac_f32_e32 v162, v36, v36
	v_fmac_f32_e32 v163, v38, v38
	v_mul_f32_e32 v161, v43, v43
	v_mul_f32_e32 v165, v35, v35
	v_fmac_f32_e32 v160, v40, v40
	v_fmac_f32_e32 v164, v32, v32
	v_add_f32_e32 v158, v158, v159
	v_add_f32_e32 v159, v162, v163
	v_fmac_f32_e32 v161, v42, v42
	v_fmac_f32_e32 v165, v34, v34
	v_add_f32_e32 v158, v160, v158
	v_add_f32_e32 v159, v164, v159
	v_add_f32_e32 v158, v161, v158
	v_add_f32_e32 v159, v165, v159
	v_add_f32_e32 v158, v158, v159
	ds_bpermute_b32 v159, v181, v158
	s_waitcnt lgkmcnt(0)
	v_add_f32_e32 v158, v158, v159
	ds_bpermute_b32 v159, v182, v158
	s_and_saveexec_b64 s[26:27], s[2:3]
	s_cbranch_execz .LBB0_1448
	s_waitcnt lgkmcnt(0)
	v_add_f32_e32 v158, v158, v159
	ds_write_b32 v210, v158
;     __device__ __forceinline__ void operator()(Acc& acc, const Unit& u, int wr, int wc, int fr, int fq) const {
;     ...
;                 const int rt = rt0 + ai * HALF + m * 16; float sq = 0.f;
; #pragma unroll
;                 for (int bj = 0; bj < 2; ++bj) {
;                     const size_t off = (size_t)(u.pm * BM + rt) * DM + col0 + bj * HALF;
;                     const f32x4 b0 = *(const f32x4*)(base + off), b1 = *(const f32x4*)(base + off + 4);
;                     const f32x4 x0 = b0 + acc[ai][bj][m][0] * alpha, x1 = b1 + acc[ai][bj][m][1] * alpha;
;                     acc[ai][bj][m][0] = x0; acc[ai][bj][m][1] = x1;
;                     sq += (x0[0] * x0[0] + x0[1] * x0[1]) + (x0[2] * x0[2] + x0[3] * x0[3]) + (x1[0] * x1[0] + x1[1] * x1[1]) + (x1[2] * x1[2] + x1[3] * x1[3]);
;                 }
;                 sq += __shfl_xor(sq, 16); sq += __shfl_xor(sq, 32);
;                 if (fq == 0) P[rt * 4 + wc] = sq;
.LBB0_1448:
	s_or_b64 exec, exec, s[26:27]
	v_add_u32_e32 v158, s25, v191
	s_waitcnt lgkmcnt(0)
	v_ashrrev_i32_e32 v159, 31, v158
	v_lshlrev_b64 v[158:159], 12, v[158:159]
	v_lshl_add_u64 v[158:159], s[82:83], 0, v[158:159]
	v_lshl_add_u64 v[158:159], v[154:155], 2, v[158:159]
	global_load_dwordx4 v[160:163], v[158:159], off nt
	global_load_dwordx4 v[164:167], v[158:159], off offset:16 nt
	global_load_dwordx4 v[168:171], v[158:159], off offset:512 nt
	global_load_dwordx4 v[172:175], v[158:159], off offset:528 nt
	s_waitcnt vmcnt(3)
	v_pk_fma_f32 v[30:31], v[30:31], 0.5, v[162:163] op_sel_hi:[1,0,1]
	v_pk_fma_f32 v[28:29], v[28:29], 0.5, v[160:161] op_sel_hi:[1,0,1]
	s_waitcnt vmcnt(1)
	v_pk_fma_f32 v[22:23], v[22:23], 0.5, v[170:171] op_sel_hi:[1,0,1]
	v_pk_fma_f32 v[20:21], v[20:21], 0.5, v[168:169] op_sel_hi:[1,0,1]
	v_pk_fma_f32 v[24:25], v[24:25], 0.5, v[164:165] op_sel_hi:[1,0,1]
	s_waitcnt vmcnt(0)
	v_pk_fma_f32 v[16:17], v[16:17], 0.5, v[172:173] op_sel_hi:[1,0,1]
	v_mul_f32_e32 v160, v29, v29
	v_mul_f32_e32 v161, v31, v31
	v_mul_f32_e32 v164, v21, v21
	v_mul_f32_e32 v165, v23, v23
	v_pk_fma_f32 v[26:27], v[26:27], 0.5, v[166:167] op_sel_hi:[1,0,1]
	v_pk_fma_f32 v[18:19], v[18:19], 0.5, v[174:175] op_sel_hi:[1,0,1]
	v_mul_f32_e32 v162, v25, v25
	v_mul_f32_e32 v166, v17, v17
	v_fmac_f32_e32 v160, v28, v28
	v_fmac_f32_e32 v161, v30, v30
	v_fmac_f32_e32 v164, v20, v20
	v_fmac_f32_e32 v165, v22, v22
	v_mul_f32_e32 v163, v27, v27
	v_mul_f32_e32 v167, v19, v19
	v_fmac_f32_e32 v162, v24, v24
	v_fmac_f32_e32 v166, v16, v16
	v_add_f32_e32 v160, v160, v161
	v_add_f32_e32 v161, v164, v165
	v_fmac_f32_e32 v163, v26, v26
	v_fmac_f32_e32 v167, v18, v18
	v_add_f32_e32 v160, v162, v160
	v_add_f32_e32 v161, v166, v161
	v_add_f32_e32 v160, v163, v160
	v_add_f32_e32 v161, v167, v161
	v_add_f32_e32 v160, v160, v161
	ds_bpermute_b32 v161, v181, v160
	s_waitcnt lgkmcnt(0)
	v_add_f32_e32 v160, v160, v161
	ds_bpermute_b32 v161, v182, v160
	s_and_saveexec_b64 s[26:27], s[2:3]
	s_cbranch_execz .LBB0_1450
	s_waitcnt lgkmcnt(0)
	v_add_f32_e32 v160, v160, v161
	ds_write_b32 v211, v160
.LBB0_1450:
	s_or_b64 exec, exec, s[26:27]
	v_add_u32_e32 v160, s25, v192
	s_waitcnt lgkmcnt(0)
	v_ashrrev_i32_e32 v161, 31, v160
	v_lshlrev_b64 v[160:161], 12, v[160:161]
	v_lshl_add_u64 v[160:161], s[82:83], 0, v[160:161]
	v_lshl_add_u64 v[160:161], v[154:155], 2, v[160:161]
	global_load_dwordx4 v[162:165], v[160:161], off nt
	global_load_dwordx4 v[166:169], v[160:161], off offset:16 nt
	global_load_dwordx4 v[216:219], v[160:161], off offset:512 nt
	global_load_dwordx4 v[220:223], v[160:161], off offset:528 nt
	s_waitcnt vmcnt(3)
	v_pk_fma_f32 v[174:175], v[14:15], 0.5, v[164:165] op_sel_hi:[1,0,1]
	v_pk_fma_f32 v[176:177], v[12:13], 0.5, v[162:163] op_sel_hi:[1,0,1]
	s_waitcnt vmcnt(2)
	v_pk_fma_f32 v[170:171], v[10:11], 0.5, v[168:169] op_sel_hi:[1,0,1]
	v_pk_fma_f32 v[172:173], v[8:9], 0.5, v[166:167] op_sel_hi:[1,0,1]
	s_waitcnt vmcnt(1)
	v_pk_fma_f32 v[166:167], v[6:7], 0.5, v[218:219] op_sel_hi:[1,0,1]
	v_pk_fma_f32 v[168:169], v[4:5], 0.5, v[216:217] op_sel_hi:[1,0,1]
	s_waitcnt vmcnt(0)
	v_pk_fma_f32 v[164:165], v[0:1], 0.5, v[220:221] op_sel_hi:[1,0,1]
	v_mul_f32_e32 v0, v177, v177
	v_mul_f32_e32 v1, v175, v175
	v_mul_f32_e32 v4, v169, v169
	v_mul_f32_e32 v5, v167, v167
	v_pk_fma_f32 v[162:163], v[2:3], 0.5, v[222:223] op_sel_hi:[1,0,1]
	v_mul_f32_e32 v2, v173, v173
	v_mul_f32_e32 v6, v165, v165
	v_fmac_f32_e32 v0, v176, v176
	v_fmac_f32_e32 v1, v174, v174
	v_fmac_f32_e32 v4, v168, v168
	v_fmac_f32_e32 v5, v166, v166
	v_mul_f32_e32 v3, v171, v171
	v_mul_f32_e32 v7, v163, v163
	v_fmac_f32_e32 v2, v172, v172
	v_fmac_f32_e32 v6, v164, v164
	v_add_f32_e32 v0, v0, v1
	v_add_f32_e32 v1, v4, v5
	v_fmac_f32_e32 v3, v170, v170
	v_fmac_f32_e32 v7, v162, v162
	v_add_f32_e32 v0, v2, v0
	v_add_f32_e32 v1, v6, v1
	v_add_f32_e32 v0, v3, v0
	v_add_f32_e32 v1, v7, v1
	v_add_f32_e32 v0, v0, v1
	ds_bpermute_b32 v1, v181, v0
	s_waitcnt lgkmcnt(0)
	v_add_f32_e32 v0, v0, v1
	ds_bpermute_b32 v1, v182, v0
	s_and_saveexec_b64 s[26:27], s[2:3]
	s_cbranch_execz .LBB0_1452
	s_waitcnt lgkmcnt(0)
	v_add_f32_e32 v0, v0, v1
	ds_write_b32 v212, v0
